# indexer tile loop hand-rewritten (128-key super-tiles, pipelined relu-sum, 4-tile prefetch) + score-row prefetch before select's serialized loads
# speedup vs baseline: 1.0069x; 1.0069x over previous
; #define PG8_STAGE(bufoff, gbase, voff) do { _Pragma("unroll") for (int _i = 0; _i < 2; ++_i) \
;         __builtin_amdgcn_global_load_lds((const unsigned*)((const char*)(gbase) + (voff)[_i]), (PG8_LAS unsigned*)(lds + (bufoff) + ldsw + _i * 8192), 16, 0, 0); } while (0)
; #define PG8_LDA(dst, b, h) do { _Pragma("unroll") for (int m = 0; m < 4; ++m) _Pragma("unroll") for (int k = 0; k < 2; ++k) dst[m][k] = *(const PG8_LAS bf16x8*)(lds + PG8_SA(b, h) + aoff + m * 2048 + k * 1024); } while (0)
; #define PG8_LDB(dst, b, h) do { _Pragma("unroll") for (int n = 0; n < 2; ++n) _Pragma("unroll") for (int k = 0; k < 2; ++k) dst[n][k] = *(const PG8_LAS bf16x8*)(lds + PG8_SB(b, h) + boff + n * 2048 + k * 1024); } while (0)
; #define PG8_MMA(ai, bj, At, Bt) do { __builtin_amdgcn_s_setprio(1); _Pragma("unroll") for (int m = 0; m < 4; ++m) _Pragma("unroll") for (int n = 0; n < 2; ++n) _Pragma("unroll") for (int k = 0; k < 2; ++k) \
;         acc[ai][bj][m][n] = __builtin_amdgcn_mfma_f32_16x16x32_bf16(Bt[n][k], At[m][k], acc[ai][bj][m][n], 0, 0, 0); __builtin_amdgcn_s_setprio(0); } while (0)
; #define PG8_WAIT_V(n) asm volatile("s_waitcnt vmcnt(" #n ")" ::: "memory")
; #define PG8_WAIT_L(n) asm volatile("s_waitcnt lgkmcnt(" #n ")" ::: "memory")
; #define PG8_BAR __builtin_amdgcn_s_barrier()
; #define PG8_SCHED __builtin_amdgcn_sched_barrier(0)
; template <class Epi, class Sched, bool ALIGN_EPI = false, bool SP2 = false>
; __device__ __forceinline__ void gemm_phase(PG8_LAS unsigned char* lds, const Gemm g, const Sched& S, const Epi& E, const int wid) {
;     ...
;             PG8_LDB(B0, 0, 0); PG8_LDB(B1, 0, 1); PG8_SCHED; PG8_LDA(At, 0, 0); PG8_STAGE(PG8_SA(1, 1), a1 + hstep, voffA);
;             PG8_WAIT_V(8); PG8_WAIT_L(0); PG8_BAR; PG8_MMA(0, 0, At, B0); PG8_MMA(0, 1, At, B1); PG8_BAR; PG8_SCHED;
;             PG8_LDA(At, 0, 1); PG8_STAGE(PG8_SB(0, 0), b2, voffB); PG8_STAGE(PG8_SB(0, 1), b2 + hstep, voffB); PG8_STAGE(PG8_SA(0, 0), a2, voffA);
;             PG8_WAIT_V(8); PG8_WAIT_L(0); PG8_BAR; PG8_MMA(1, 0, At, B0); PG8_MMA(1, 1, At, B1); PG8_BAR; PG8_SCHED;
.LBB0_277:
	ds_read_b128 v[128:131], v163
	ds_read_b128 v[132:135], v163 offset:1024
	ds_read_b128 v[136:139], v163 offset:2048
	ds_read_b128 v[140:143], v163 offset:3072
	ds_read_b128 v[168:171], v165
	s_nop 0
	ds_read_b128 v[172:175], v165 offset:1024
	ds_read_b128 v[176:179], v165 offset:2048
	ds_read_b128 v[180:183], v165 offset:3072
	s_add_u32 s62, s60, 0xfff00080
	s_addc_u32 s63, s61, -1
	s_cmp_eq_u32 s70, 60
	s_cselect_b32 s67, s53, s63
	s_cselect_b32 s66, s59, s62
	s_cselect_b32 s63, s51, s69
	s_cselect_b32 s62, s65, s68
	v_lshl_add_u64 v[216:217], s[60:61], 0, v[152:153]
	s_add_i32 m0, s76, 0xc000
	ds_read_b128 v[184:187], v167
	ds_read_b128 v[188:191], v167 offset:1024
	ds_read_b128 v[192:195], v167 offset:2048
	ds_read_b128 v[196:199], v167 offset:3072
	ds_read_b128 v[200:203], v167 offset:4096
	ds_read_b128 v[204:207], v167 offset:5120
	ds_read_b128 v[208:211], v167 offset:6144
	ds_read_b128 v[212:215], v167 offset:7168
	global_load_lds_dwordx4 v[216:217], off
	v_lshl_add_u64 v[216:217], s[60:61], 0, v[154:155]
	s_add_i32 m0, s76, 0xe000
	s_nop 0
	global_load_lds_dwordx4 v[216:217], off
	s_waitcnt vmcnt(8)
	s_waitcnt lgkmcnt(0)
	s_barrier
	s_setprio 1
	s_waitcnt lgkmcnt(0)
	v_mfma_f32_16x16x32_bf16 v[124:127], v[128:131], v[184:187], v[124:127]
	v_mfma_f32_16x16x32_bf16 v[120:123], v[136:139], v[184:187], v[120:123]
	v_mfma_f32_16x16x32_bf16 v[108:111], v[128:131], v[192:195], v[108:111]
	v_mfma_f32_16x16x32_bf16 v[104:107], v[136:139], v[192:195], v[104:107]
	v_mfma_f32_16x16x32_bf16 v[92:95], v[128:131], v[200:203], v[92:95]
	v_mfma_f32_16x16x32_bf16 v[88:91], v[136:139], v[200:203], v[88:91]
	v_mfma_f32_16x16x32_bf16 v[76:79], v[128:131], v[208:211], v[76:79]
	v_mfma_f32_16x16x32_bf16 v[72:75], v[136:139], v[208:211], v[72:75]
	v_mfma_f32_16x16x32_bf16 v[124:127], v[132:135], v[188:191], v[124:127]
	v_mfma_f32_16x16x32_bf16 v[120:123], v[140:143], v[188:191], v[120:123]
	v_mfma_f32_16x16x32_bf16 v[108:111], v[132:135], v[196:199], v[108:111]
	v_mfma_f32_16x16x32_bf16 v[104:107], v[140:143], v[196:199], v[104:107]
	v_mfma_f32_16x16x32_bf16 v[92:95], v[132:135], v[204:207], v[92:95]
	v_mfma_f32_16x16x32_bf16 v[88:91], v[140:143], v[204:207], v[88:91]
	v_mfma_f32_16x16x32_bf16 v[76:79], v[132:135], v[212:215], v[76:79]
	v_mfma_f32_16x16x32_bf16 v[72:75], v[140:143], v[212:215], v[72:75]
	s_setprio 0
	s_setprio 1
	v_mfma_f32_16x16x32_bf16 v[116:119], v[168:171], v[184:187], v[116:119]
	v_mfma_f32_16x16x32_bf16 v[112:115], v[176:179], v[184:187], v[112:115]
	v_mfma_f32_16x16x32_bf16 v[100:103], v[168:171], v[192:195], v[100:103]
	v_mfma_f32_16x16x32_bf16 v[96:99], v[176:179], v[192:195], v[96:99]
	v_mfma_f32_16x16x32_bf16 v[84:87], v[168:171], v[200:203], v[84:87]
	v_mfma_f32_16x16x32_bf16 v[80:83], v[176:179], v[200:203], v[80:83]
	v_mfma_f32_16x16x32_bf16 v[68:71], v[168:171], v[208:211], v[68:71]
	v_mfma_f32_16x16x32_bf16 v[64:67], v[176:179], v[208:211], v[64:67]
	v_mfma_f32_16x16x32_bf16 v[116:119], v[172:175], v[188:191], v[116:119]
	v_mfma_f32_16x16x32_bf16 v[112:115], v[180:183], v[188:191], v[112:115]
	v_mfma_f32_16x16x32_bf16 v[100:103], v[172:175], v[196:199], v[100:103]
	v_mfma_f32_16x16x32_bf16 v[96:99], v[180:183], v[196:199], v[96:99]
	v_mfma_f32_16x16x32_bf16 v[84:87], v[172:175], v[204:207], v[84:87]
	v_mfma_f32_16x16x32_bf16 v[80:83], v[180:183], v[204:207], v[80:83]
	v_mfma_f32_16x16x32_bf16 v[68:71], v[172:175], v[212:215], v[68:71]
	v_mfma_f32_16x16x32_bf16 v[64:67], v[180:183], v[212:215], v[64:67]
	s_setprio 0
	s_barrier
	s_add_i32 s71, s89, s75
	v_lshl_add_u64 v[216:217], s[62:63], 0, v[146:147]
	s_mov_b32 m0, s71
	ds_read_b128 v[184:187], v167 offset:16384
	ds_read_b128 v[188:191], v167 offset:17408
	ds_read_b128 v[192:195], v167 offset:18432
	ds_read_b128 v[196:199], v167 offset:19456
	ds_read_b128 v[200:203], v167 offset:20480
	ds_read_b128 v[204:207], v167 offset:21504
	ds_read_b128 v[208:211], v167 offset:22528
	ds_read_b128 v[212:215], v167 offset:23552
	global_load_lds_dwordx4 v[216:217], off
	s_add_i32 m0, s71, 0x2000
	s_add_u32 s72, s62, 0x100000
	v_lshl_add_u64 v[218:219], s[62:63], 0, v[150:151]
	s_addc_u32 s73, s63, 0
	s_add_i32 s71, s90, s75
	global_load_lds_dwordx4 v[218:219], off
	v_lshl_add_u64 v[220:221], s[72:73], 0, v[146:147]
	s_mov_b32 m0, s71
	v_lshl_add_u64 v[222:223], s[66:67], 0, v[148:149]
	global_load_lds_dwordx4 v[220:221], off
	v_lshl_add_u64 v[220:221], s[72:73], 0, v[150:151]
	s_add_i32 m0, s71, 0x2000
	s_nop 0
	global_load_lds_dwordx4 v[220:221], off
	v_lshl_add_u64 v[220:221], s[66:67], 0, v[144:145]
	s_mov_b32 m0, s76
	s_nop 0
	global_load_lds_dwordx4 v[220:221], off
	s_mov_b32 m0, s77
	s_nop 0
	global_load_lds_dwordx4 v[222:223], off
	s_waitcnt vmcnt(8)
	s_waitcnt lgkmcnt(0)
	s_barrier
; #define PG8_STAGE(bufoff, gbase, voff) do { _Pragma("unroll") for (int _i = 0; _i < 2; ++_i) \
;         __builtin_amdgcn_global_load_lds((const unsigned*)((const char*)(gbase) + (voff)[_i]), (PG8_LAS unsigned*)(lds + (bufoff) + ldsw + _i * 8192), 16, 0, 0); } while (0)
; #define PG8_LDA(dst, b, h) do { _Pragma("unroll") for (int m = 0; m < 4; ++m) _Pragma("unroll") for (int k = 0; k < 2; ++k) dst[m][k] = *(const PG8_LAS bf16x8*)(lds + PG8_SA(b, h) + aoff + m * 2048 + k * 1024); } while (0)
; #define PG8_LDB(dst, b, h) do { _Pragma("unroll") for (int n = 0; n < 2; ++n) _Pragma("unroll") for (int k = 0; k < 2; ++k) dst[n][k] = *(const PG8_LAS bf16x8*)(lds + PG8_SB(b, h) + boff + n * 2048 + k * 1024); } while (0)
; #define PG8_MMA(ai, bj, At, Bt) do { __builtin_amdgcn_s_setprio(1); _Pragma("unroll") for (int m = 0; m < 4; ++m) _Pragma("unroll") for (int n = 0; n < 2; ++n) _Pragma("unroll") for (int k = 0; k < 2; ++k) \
;         acc[ai][bj][m][n] = __builtin_amdgcn_mfma_f32_16x16x32_bf16(Bt[n][k], At[m][k], acc[ai][bj][m][n], 0, 0, 0); __builtin_amdgcn_s_setprio(0); } while (0)
; #define PG8_WAIT_V(n) asm volatile("s_waitcnt vmcnt(" #n ")" ::: "memory")
; #define PG8_WAIT_L(n) asm volatile("s_waitcnt lgkmcnt(" #n ")" ::: "memory")
; #define PG8_BAR __builtin_amdgcn_s_barrier()
; #define PG8_SCHED __builtin_amdgcn_sched_barrier(0)
; template <class Epi, class Sched, bool ALIGN_EPI = false, bool SP2 = false>
; __device__ __forceinline__ void gemm_phase(PG8_LAS unsigned char* lds, const Gemm g, const Sched& S, const Epi& E, const int wid) {
;     ...
;             PG8_WAIT_V(8); PG8_WAIT_L(0); PG8_BAR; PG8_MMA(1, 0, At, B0); PG8_MMA(1, 1, At, B1); PG8_BAR; PG8_SCHED;
;             PG8_LDB(B0, 1, 0); PG8_LDB(B1, 1, 1); PG8_SCHED; PG8_LDA(At, 1, 0); PG8_STAGE(PG8_SA(0, 1), a2 + hstep, voffA);
;             PG8_WAIT_V(8); PG8_WAIT_L(0); PG8_BAR; PG8_MMA(0, 0, At, B0); PG8_MMA(0, 1, At, B1); PG8_BAR; PG8_SCHED;
	s_setprio 1
	s_waitcnt lgkmcnt(0)
	v_mfma_f32_16x16x32_bf16 v[60:63], v[128:131], v[184:187], v[60:63]
	v_mfma_f32_16x16x32_bf16 v[56:59], v[136:139], v[184:187], v[56:59]
	v_mfma_f32_16x16x32_bf16 v[44:47], v[128:131], v[192:195], v[44:47]
	v_mfma_f32_16x16x32_bf16 v[40:43], v[136:139], v[192:195], v[40:43]
	v_mfma_f32_16x16x32_bf16 v[28:31], v[128:131], v[200:203], v[28:31]
	v_mfma_f32_16x16x32_bf16 v[24:27], v[136:139], v[200:203], v[24:27]
	v_mfma_f32_16x16x32_bf16 v[12:15], v[128:131], v[208:211], v[12:15]
	v_mfma_f32_16x16x32_bf16 v[8:11], v[136:139], v[208:211], v[8:11]
	v_mfma_f32_16x16x32_bf16 v[60:63], v[132:135], v[188:191], v[60:63]
	v_mfma_f32_16x16x32_bf16 v[56:59], v[140:143], v[188:191], v[56:59]
	v_mfma_f32_16x16x32_bf16 v[44:47], v[132:135], v[196:199], v[44:47]
	v_mfma_f32_16x16x32_bf16 v[40:43], v[140:143], v[196:199], v[40:43]
	v_mfma_f32_16x16x32_bf16 v[28:31], v[132:135], v[204:207], v[28:31]
	v_mfma_f32_16x16x32_bf16 v[24:27], v[140:143], v[204:207], v[24:27]
	v_mfma_f32_16x16x32_bf16 v[12:15], v[132:135], v[212:215], v[12:15]
	v_mfma_f32_16x16x32_bf16 v[8:11], v[140:143], v[212:215], v[8:11]
	s_setprio 0
	s_setprio 1
	v_mfma_f32_16x16x32_bf16 v[52:55], v[168:171], v[184:187], v[52:55]
	v_mfma_f32_16x16x32_bf16 v[48:51], v[176:179], v[184:187], v[48:51]
	v_mfma_f32_16x16x32_bf16 v[36:39], v[168:171], v[192:195], v[36:39]
	v_mfma_f32_16x16x32_bf16 v[32:35], v[176:179], v[192:195], v[32:35]
	v_mfma_f32_16x16x32_bf16 v[20:23], v[168:171], v[200:203], v[20:23]
	v_mfma_f32_16x16x32_bf16 v[16:19], v[176:179], v[200:203], v[16:19]
	v_mfma_f32_16x16x32_bf16 v[4:7], v[168:171], v[208:211], v[4:7]
	v_mfma_f32_16x16x32_bf16 v[0:3], v[176:179], v[208:211], v[0:3]
	v_mfma_f32_16x16x32_bf16 v[52:55], v[172:175], v[188:191], v[52:55]
	v_mfma_f32_16x16x32_bf16 v[48:51], v[180:183], v[188:191], v[48:51]
	v_mfma_f32_16x16x32_bf16 v[36:39], v[172:175], v[196:199], v[36:39]
	v_mfma_f32_16x16x32_bf16 v[32:35], v[180:183], v[196:199], v[32:35]
	v_mfma_f32_16x16x32_bf16 v[20:23], v[172:175], v[204:207], v[20:23]
	v_mfma_f32_16x16x32_bf16 v[16:19], v[180:183], v[204:207], v[16:19]
	v_mfma_f32_16x16x32_bf16 v[4:7], v[172:175], v[212:215], v[4:7]
	v_mfma_f32_16x16x32_bf16 v[0:3], v[180:183], v[212:215], v[0:3]
	s_setprio 0
	s_barrier
	s_add_i32 s71, 0, 0x18000
	s_add_i32 s72, 0, 0x1c000
	v_add_u32_e32 v140, s71, v161
	v_add_u32_e32 v160, s72, v161
	ds_read_b128 v[128:131], v140
	ds_read_b128 v[132:135], v140 offset:1024
	ds_read_b128 v[136:139], v140 offset:2048
	ds_read_b128 v[140:143], v140 offset:3072
	ds_read_b128 v[168:171], v160
	ds_read_b128 v[172:175], v160 offset:1024
	ds_read_b128 v[176:179], v160 offset:2048
	ds_read_b128 v[180:183], v160 offset:3072
	s_add_u32 s66, s66, 0x100000
	s_addc_u32 s67, s67, 0
	s_mov_b32 m0, s78
	v_lshl_add_u64 v[224:225], s[66:67], 0, v[144:145]
	ds_read_b128 v[184:187], v167 offset:32768
	ds_read_b128 v[188:191], v167 offset:33792
	ds_read_b128 v[192:195], v167 offset:34816
	ds_read_b128 v[196:199], v167 offset:35840
	ds_read_b128 v[200:203], v167 offset:36864
	ds_read_b128 v[204:207], v167 offset:37888
	ds_read_b128 v[208:211], v167 offset:38912
	ds_read_b128 v[212:215], v167 offset:39936
	global_load_lds_dwordx4 v[224:225], off
	v_lshl_add_u64 v[224:225], s[66:67], 0, v[148:149]
	s_mov_b32 m0, s79
	s_nop 0
	global_load_lds_dwordx4 v[224:225], off
	s_waitcnt vmcnt(8)
	s_waitcnt lgkmcnt(0)
	s_barrier
	s_setprio 1
	s_waitcnt lgkmcnt(0)
	v_mfma_f32_16x16x32_bf16 v[124:127], v[128:131], v[184:187], v[124:127]
	v_mfma_f32_16x16x32_bf16 v[120:123], v[136:139], v[184:187], v[120:123]
	v_mfma_f32_16x16x32_bf16 v[108:111], v[128:131], v[192:195], v[108:111]
	v_mfma_f32_16x16x32_bf16 v[104:107], v[136:139], v[192:195], v[104:107]
	v_mfma_f32_16x16x32_bf16 v[92:95], v[128:131], v[200:203], v[92:95]
	v_mfma_f32_16x16x32_bf16 v[88:91], v[136:139], v[200:203], v[88:91]
	v_mfma_f32_16x16x32_bf16 v[76:79], v[128:131], v[208:211], v[76:79]
	v_mfma_f32_16x16x32_bf16 v[72:75], v[136:139], v[208:211], v[72:75]
	v_mfma_f32_16x16x32_bf16 v[124:127], v[132:135], v[188:191], v[124:127]
	v_mfma_f32_16x16x32_bf16 v[120:123], v[140:143], v[188:191], v[120:123]
	v_mfma_f32_16x16x32_bf16 v[108:111], v[132:135], v[196:199], v[108:111]
	v_mfma_f32_16x16x32_bf16 v[104:107], v[140:143], v[196:199], v[104:107]
	v_mfma_f32_16x16x32_bf16 v[92:95], v[132:135], v[204:207], v[92:95]
	v_mfma_f32_16x16x32_bf16 v[88:91], v[140:143], v[204:207], v[88:91]
	v_mfma_f32_16x16x32_bf16 v[76:79], v[132:135], v[212:215], v[76:79]
	v_mfma_f32_16x16x32_bf16 v[72:75], v[140:143], v[212:215], v[72:75]
	s_setprio 0
	s_setprio 1
	v_mfma_f32_16x16x32_bf16 v[116:119], v[168:171], v[184:187], v[116:119]
	v_mfma_f32_16x16x32_bf16 v[112:115], v[176:179], v[184:187], v[112:115]
	v_mfma_f32_16x16x32_bf16 v[100:103], v[168:171], v[192:195], v[100:103]
	v_mfma_f32_16x16x32_bf16 v[96:99], v[176:179], v[192:195], v[96:99]
	v_mfma_f32_16x16x32_bf16 v[84:87], v[168:171], v[200:203], v[84:87]
	v_mfma_f32_16x16x32_bf16 v[80:83], v[176:179], v[200:203], v[80:83]
	v_mfma_f32_16x16x32_bf16 v[68:71], v[168:171], v[208:211], v[68:71]
	v_mfma_f32_16x16x32_bf16 v[64:67], v[176:179], v[208:211], v[64:67]
	v_mfma_f32_16x16x32_bf16 v[116:119], v[172:175], v[188:191], v[116:119]
	v_mfma_f32_16x16x32_bf16 v[112:115], v[180:183], v[188:191], v[112:115]
	v_mfma_f32_16x16x32_bf16 v[100:103], v[172:175], v[196:199], v[100:103]
	v_mfma_f32_16x16x32_bf16 v[96:99], v[180:183], v[196:199], v[96:99]
	v_mfma_f32_16x16x32_bf16 v[84:87], v[172:175], v[204:207], v[84:87]
	v_mfma_f32_16x16x32_bf16 v[80:83], v[180:183], v[204:207], v[80:83]
	v_mfma_f32_16x16x32_bf16 v[68:71], v[172:175], v[212:215], v[68:71]
	v_mfma_f32_16x16x32_bf16 v[64:67], v[180:183], v[212:215], v[64:67]
	s_setprio 0
	s_barrier
; #define PG8_STAGE(bufoff, gbase, voff) do { _Pragma("unroll") for (int _i = 0; _i < 2; ++_i) \
;         __builtin_amdgcn_global_load_lds((const unsigned*)((const char*)(gbase) + (voff)[_i]), (PG8_LAS unsigned*)(lds + (bufoff) + ldsw + _i * 8192), 16, 0, 0); } while (0)
; #define PG8_LDA(dst, b, h) do { _Pragma("unroll") for (int m = 0; m < 4; ++m) _Pragma("unroll") for (int k = 0; k < 2; ++k) dst[m][k] = *(const PG8_LAS bf16x8*)(lds + PG8_SA(b, h) + aoff + m * 2048 + k * 1024); } while (0)
; #define PG8_MMA(ai, bj, At, Bt) do { __builtin_amdgcn_s_setprio(1); _Pragma("unroll") for (int m = 0; m < 4; ++m) _Pragma("unroll") for (int n = 0; n < 2; ++n) _Pragma("unroll") for (int k = 0; k < 2; ++k) \
;         acc[ai][bj][m][n] = __builtin_amdgcn_mfma_f32_16x16x32_bf16(Bt[n][k], At[m][k], acc[ai][bj][m][n], 0, 0, 0); __builtin_amdgcn_s_setprio(0); } while (0)
; #define PG8_WAIT_V(n) asm volatile("s_waitcnt vmcnt(" #n ")" ::: "memory")
; #define PG8_WAIT_L(n) asm volatile("s_waitcnt lgkmcnt(" #n ")" ::: "memory")
; #define PG8_BAR __builtin_amdgcn_s_barrier()
; #define PG8_SCHED __builtin_amdgcn_sched_barrier(0)
; template <class Epi, class Sched, bool ALIGN_EPI = false, bool SP2 = false>
; __device__ __forceinline__ void gemm_phase(PG8_LAS unsigned char* lds, const Gemm g, const Sched& S, const Epi& E, const int wid) {
;     ...
;             PG8_LDA(At, 1, 1); PG8_STAGE(PG8_SB(1, 0), b3, voffB); PG8_STAGE(PG8_SB(1, 1), b3 + hstep, voffB); PG8_STAGE(PG8_SA(1, 0), a3, voffA);
;             PG8_WAIT_V(8); PG8_WAIT_L(0); PG8_BAR; PG8_MMA(1, 0, At, B0); PG8_MMA(1, 1, At, B1); PG8_BAR; PG8_SCHED;
;     ...
;         if constexpr (ALIGN_EPI) { if (wr == 0) PG8_BAR; }
	s_add_i32 s66, s71, s75
	v_lshl_add_u64 v[216:217], v[216:217], 0, s[40:41]
	s_mov_b32 m0, s66
	ds_read_b128 v[184:187], v167 offset:49152
	ds_read_b128 v[188:191], v167 offset:50176
	ds_read_b128 v[192:195], v167 offset:51200
	ds_read_b128 v[196:199], v167 offset:52224
	ds_read_b128 v[200:203], v167 offset:53248
	ds_read_b128 v[204:207], v167 offset:54272
	ds_read_b128 v[208:211], v167 offset:55296
	ds_read_b128 v[212:215], v167 offset:56320
	global_load_lds_dwordx4 v[216:217], off
	s_add_i32 m0, s66, 0x2000
	s_add_u32 s62, s62, 0x100080
	v_lshl_add_u64 v[216:217], v[218:219], 0, s[40:41]
	s_addc_u32 s63, s63, 0
	s_add_i32 s66, s72, s75
	global_load_lds_dwordx4 v[216:217], off
	v_lshl_add_u64 v[216:217], s[62:63], 0, v[146:147]
	s_mov_b32 m0, s66
	s_nop 0
	global_load_lds_dwordx4 v[216:217], off
	v_lshl_add_u64 v[216:217], s[62:63], 0, v[150:151]
	s_add_i32 m0, s66, 0x2000
	s_nop 0
	global_load_lds_dwordx4 v[216:217], off
	v_lshl_add_u64 v[216:217], v[220:221], 0, s[40:41]
	s_mov_b32 m0, s83
	s_nop 0
	global_load_lds_dwordx4 v[216:217], off
	v_lshl_add_u64 v[216:217], v[222:223], 0, s[40:41]
	s_mov_b32 m0, s84
	s_nop 0
	global_load_lds_dwordx4 v[216:217], off
	s_waitcnt vmcnt(8)
	s_waitcnt lgkmcnt(0)
	s_barrier
	s_setprio 1
	s_waitcnt lgkmcnt(0)
	v_mfma_f32_16x16x32_bf16 v[60:63], v[128:131], v[184:187], v[60:63]
	v_mfma_f32_16x16x32_bf16 v[56:59], v[136:139], v[184:187], v[56:59]
	v_mfma_f32_16x16x32_bf16 v[44:47], v[128:131], v[192:195], v[44:47]
	v_mfma_f32_16x16x32_bf16 v[40:43], v[136:139], v[192:195], v[40:43]
	v_mfma_f32_16x16x32_bf16 v[28:31], v[128:131], v[200:203], v[28:31]
	v_mfma_f32_16x16x32_bf16 v[24:27], v[136:139], v[200:203], v[24:27]
	v_mfma_f32_16x16x32_bf16 v[12:15], v[128:131], v[208:211], v[12:15]
	v_mfma_f32_16x16x32_bf16 v[8:11], v[136:139], v[208:211], v[8:11]
	v_mfma_f32_16x16x32_bf16 v[60:63], v[132:135], v[188:191], v[60:63]
	v_mfma_f32_16x16x32_bf16 v[56:59], v[140:143], v[188:191], v[56:59]
	v_mfma_f32_16x16x32_bf16 v[44:47], v[132:135], v[196:199], v[44:47]
	v_mfma_f32_16x16x32_bf16 v[40:43], v[140:143], v[196:199], v[40:43]
	v_mfma_f32_16x16x32_bf16 v[28:31], v[132:135], v[204:207], v[28:31]
	v_mfma_f32_16x16x32_bf16 v[24:27], v[140:143], v[204:207], v[24:27]
	v_mfma_f32_16x16x32_bf16 v[12:15], v[132:135], v[212:215], v[12:15]
	v_mfma_f32_16x16x32_bf16 v[8:11], v[140:143], v[212:215], v[8:11]
	s_setprio 0
	s_setprio 1
	v_mfma_f32_16x16x32_bf16 v[52:55], v[168:171], v[184:187], v[52:55]
	v_mfma_f32_16x16x32_bf16 v[48:51], v[176:179], v[184:187], v[48:51]
	v_mfma_f32_16x16x32_bf16 v[36:39], v[168:171], v[192:195], v[36:39]
	v_mfma_f32_16x16x32_bf16 v[32:35], v[176:179], v[192:195], v[32:35]
	v_mfma_f32_16x16x32_bf16 v[20:23], v[168:171], v[200:203], v[20:23]
	v_mfma_f32_16x16x32_bf16 v[16:19], v[176:179], v[200:203], v[16:19]
	v_mfma_f32_16x16x32_bf16 v[4:7], v[168:171], v[208:211], v[4:7]
	v_mfma_f32_16x16x32_bf16 v[0:3], v[176:179], v[208:211], v[0:3]
	v_mfma_f32_16x16x32_bf16 v[52:55], v[172:175], v[188:191], v[52:55]
	v_mfma_f32_16x16x32_bf16 v[48:51], v[180:183], v[188:191], v[48:51]
	v_mfma_f32_16x16x32_bf16 v[36:39], v[172:175], v[196:199], v[36:39]
	v_mfma_f32_16x16x32_bf16 v[32:35], v[180:183], v[196:199], v[32:35]
	v_mfma_f32_16x16x32_bf16 v[20:23], v[172:175], v[204:207], v[20:23]
	v_mfma_f32_16x16x32_bf16 v[16:19], v[180:183], v[204:207], v[16:19]
	v_mfma_f32_16x16x32_bf16 v[4:7], v[172:175], v[212:215], v[4:7]
	v_mfma_f32_16x16x32_bf16 v[0:3], v[180:183], v[212:215], v[0:3]
	s_setprio 0
	s_barrier
	s_add_i32 s70, s70, 2
	s_add_u32 s60, s60, 0x100
	s_addc_u32 s61, s61, 0
	s_add_u32 s68, s68, 0x100
	s_addc_u32 s69, s69, 0
	s_cmp_gt_u32 s70, 61
	s_cbranch_scc0 .LBB0_277
	s_and_b64 vcc, exec, s[42:43]
	s_cbranch_vccz .LBB0_280
	s_barrier

; #define PG8_BAR __builtin_amdgcn_s_barrier()
; template <class Epi, class Sched, bool ALIGN_EPI = false, bool SP2 = false>
; __device__ __forceinline__ void gemm_phase(PG8_LAS unsigned char* lds, const Gemm g, const Sched& S, const Epi& E, const int wid) {
;     ...
;         if constexpr (!Epi::AFTER_DRAIN) { E(acc, cur, wr, wc, fr, fq); S.done(cur); }
;         if (!has_next) break;
;         if (!Epi::CHAIN || !E.keep(cur)) {
; #pragma unroll
;         for (int a = 0; a < 2; ++a)
; #pragma unroll
;             for (int b = 0; b < 2; ++b)
; #pragma unroll
;                 for (int m = 0; m < 4; ++m)
; #pragma unroll
;                     for (int n = 0; n < 2; ++n) acc[a][b][m][n] = (f32x4){0.f, 0.f, 0.f, 0.f};
;         }
;         cur = nxt; cA = nA; cB = nB; ++ui;
;         if constexpr (ALIGN_EPI) { if (wr == 1) PG8_BAR; }
.LBB0_317:
	s_or_b64 exec, exec, s[64:65]
	s_waitcnt vmcnt(0)
	s_mov_b64 s[64:65], 0

; __device__ __forceinline__ int lane_opaque() { int l; asm volatile("v_mbcnt_lo_u32_b32 %0, -1, 0\n\tv_mbcnt_hi_u32_b32 %0, -1, %0" : "=v"(l)); return l; }
; #define LAS __attribute__((address_space(3)))
; DI void indexer_unit(unsigned char* ws, LAS unsigned char* lds, int b, int blk, float* scratch, int wave) {
;     const int lane = lane_opaque(), tid = wave * 64 + lane;
;     const bf16* qi = (const bf16*)(ws + WS_QI); const bf16* ki = (const bf16*)(ws + WS_KI); const float* wi = (const float*)(ws + WS_WI);
;     const int t0 = blk * 32, mrow0 = b * SEQ + t0;
;     const int r = lane & 31, kh = lane >> 5, aq = (r >> 2) & 1, ah = (r & 3) + 4 * (r >> 3);
;     bf16x8 af[2][8]; f32x4 wg[2][4];
; #pragma unroll
;     for (int rt = 0; rt < 2; ++rt) {
;         const bf16* src = qi + (size_t)(mrow0 + 4 * wave + 2 * rt + aq) * DIQ + ah * HDI + 8 * kh;
; #pragma unroll
;         for (int ks = 0; ks < 8; ++ks) af[rt][ks] = *(const bf16x8*)(src + 16 * ks);
;         const float* wsrc = wi + (size_t)(mrow0 + 4 * wave + 2 * rt + kh) * NHI;
; #pragma unroll
;         for (int j = 0; j < 4; ++j) wg[rt][j] = *(const f32x4*)(wsrc + 4 * j) * 0.08838834764831845f;
;     }
;     const int nk = (t0 + 32 + 63) >> 6;
;     const int lkey = tid >> 3, lpart = tid & 7;
;     const bf16* kbase = ki + (size_t)(b * SEQ) * HDI;
;     v4u st0, st1, su0, su1;
;     { const v4u* g = (const v4u*)(kbase + (size_t)lkey * HDI + lpart * 16); st0 = g[0]; st1 = g[1]; }
;     if (1 < nk) { const v4u* g = (const v4u*)(kbase + (size_t)(64 + lkey) * HDI + lpart * 16); su0 = g[0]; su1 = g[1]; }
;     __syncthreads();
;     { LAS v4u* d = (LAS v4u*)(lds + lkey * IDX_TS + lpart * 32); d[0] = st0; d[1] = st1; }
;     __syncthreads();
.LBB0_511:
	s_and_b64 s[2:3], s[0:1], exec
	v_readlane_b32 s2, v254, 43
	v_readlane_b32 s3, v254, 44
	s_cselect_b32 s2, s2, s3
	v_mbcnt_lo_u32_b32 v39, -1, 0
	v_mbcnt_hi_u32_b32 v39, -1, v39
	s_lshl_b32 s90, s2, 5
	v_and_b32_e32 v0, 3, v39
	v_lshrrev_b32_e32 v1, 1, v39
	v_ashrrev_i32_e32 v38, 5, v39
	v_and_or_b32 v0, v1, 12, v0
	v_readlane_b32 s6, v254, 27
	s_or_b32 s3, s90, s88
	v_lshlrev_b32_e32 v160, 8, v0
	v_readlane_b32 s7, v254, 28
	v_lshlrev_b32_e32 v2, 3, v38
	s_add_i32 s3, s3, s80
	v_bfe_u32 v12, v39, 2, 1
	v_lshl_add_u64 v[0:1], s[6:7], 0, v[160:161]
	v_ashrrev_i32_e32 v3, 31, v2
	v_lshl_add_u64 v[4:5], v[2:3], 1, v[0:1]
	v_or_b32_e32 v0, s3, v12
	v_ashrrev_i32_e32 v1, 31, v0
	v_lshlrev_b64 v[0:1], 12, v[0:1]
	v_lshl_add_u64 v[0:1], v[4:5], 0, v[0:1]
	global_load_dwordx4 v[48:51], v[0:1], off
	global_load_dwordx4 v[52:55], v[0:1], off offset:32
	global_load_dwordx4 v[56:59], v[0:1], off offset:64
	global_load_dwordx4 v[60:63], v[0:1], off offset:96
	global_load_dwordx4 v[64:67], v[0:1], off offset:128
	global_load_dwordx4 v[68:71], v[0:1], off offset:160
	global_load_dwordx4 v[72:75], v[0:1], off offset:192
	global_load_dwordx4 v[76:79], v[0:1], off offset:224
	v_add_u32_e32 v0, s3, v38
	v_ashrrev_i32_e32 v1, 31, v0
	v_readlane_b32 s6, v254, 29
	v_lshlrev_b64 v[0:1], 6, v[0:1]
	v_readlane_b32 s7, v254, 30
	s_or_b32 s4, s3, 2
	v_readlane_b32 s3, v254, 11
	v_lshl_add_u64 v[6:7], s[6:7], 0, v[0:1]
	global_load_dwordx4 v[0:3], v[6:7], off offset:48
	global_load_dwordx4 v[8:11], v[6:7], off offset:32
	global_load_dwordx4 v[16:19], v[6:7], off offset:16
	global_load_dwordx4 v[24:27], v[6:7], off
	v_or_b32_e32 v6, s4, v12
	v_ashrrev_i32_e32 v7, 31, v6
	v_lshlrev_b64 v[6:7], 12, v[6:7]
	v_lshl_add_u64 v[4:5], v[4:5], 0, v[6:7]
	global_load_dwordx4 v[80:83], v[4:5], off
	global_load_dwordx4 v[84:87], v[4:5], off offset:32
	global_load_dwordx4 v[88:91], v[4:5], off offset:64
	global_load_dwordx4 v[92:95], v[4:5], off offset:96
	global_load_dwordx4 v[96:99], v[4:5], off offset:128
	global_load_dwordx4 v[100:103], v[4:5], off offset:160
	global_load_dwordx4 v[104:107], v[4:5], off offset:192
	global_load_dwordx4 v[108:111], v[4:5], off offset:224
	v_add_u32_e32 v4, s4, v38
	v_add_u32_e32 v32, s3, v39
	v_ashrrev_i32_e32 v5, 31, v4
	v_ashrrev_i32_e32 v34, 3, v32
	v_lshlrev_b64 v[4:5], 6, v[4:5]
	v_ashrrev_i32_e32 v35, 31, v34
	v_readlane_b32 s4, v254, 46
	v_lshl_add_u64 v[28:29], s[6:7], 0, v[4:5]
	v_and_b32_e32 v40, 7, v39
	v_lshlrev_b64 v[32:33], 8, v[34:35]
	v_readlane_b32 s5, v254, 47
	global_load_dwordx4 v[4:7], v[28:29], off offset:48
	global_load_dwordx4 v[12:15], v[28:29], off offset:32
	global_load_dwordx4 v[20:23], v[28:29], off offset:16
	s_nop 0
	global_load_dwordx4 v[28:31], v[28:29], off
	v_lshl_add_u64 v[36:37], s[4:5], 0, v[32:33]
	v_lshlrev_b32_e32 v160, 5, v40
	v_lshl_add_u64 v[42:43], v[36:37], 0, v[160:161]
	global_load_dwordx4 v[116:119], v[42:43], off offset:16
	global_load_dwordx4 v[112:115], v[42:43], off
	s_mov_b64 s[98:99], 0x4000
	v_lshl_add_u64 v[230:231], v[42:43], 0, s[98:99]
	global_load_dwordx4 v[120:123], v[230:231], off
	global_load_dwordx4 v[124:127], v[230:231], off offset:16
	v_lshl_add_u64 v[230:231], v[230:231], 0, s[98:99]
	global_load_dwordx4 v[214:217], v[230:231], off
	global_load_dwordx4 v[218:221], v[230:231], off offset:16
	v_lshl_add_u64 v[230:231], v[230:231], 0, s[98:99]
	global_load_dwordx4 v[222:225], v[230:231], off
	global_load_dwordx4 v[226:229], v[230:231], off offset:16
	v_lshl_add_u64 v[230:231], v[230:231], 0, s[98:99]
.LBB0_513:
	s_xor_b64 s[0:1], s[0:1], -1
	v_writelane_b32 v254, s0, 51
	s_mov_b32 s8, 0
	s_nop 0
	v_writelane_b32 v254, s1, 52
	s_add_i32 s0, s90, 0x5f
	s_lshr_b32 s6, s0, 6
	s_mov_b32 s0, 0x3db504f3
	s_waitcnt vmcnt(14)
	v_pk_mul_f32 v[130:131], v[26:27], s[0:1] op_sel_hi:[1,0]
	v_pk_mul_f32 v[128:129], v[24:25], s[0:1] op_sel_hi:[1,0]
	v_pk_mul_f32 v[134:135], v[18:19], s[0:1] op_sel_hi:[1,0]
	v_pk_mul_f32 v[132:133], v[16:17], s[0:1] op_sel_hi:[1,0]
	v_pk_mul_f32 v[138:139], v[10:11], s[0:1] op_sel_hi:[1,0]
	v_pk_mul_f32 v[136:137], v[8:9], s[0:1] op_sel_hi:[1,0]
	v_pk_mul_f32 v[142:143], v[2:3], s[0:1] op_sel_hi:[1,0]
	v_pk_mul_f32 v[140:141], v[0:1], s[0:1] op_sel_hi:[1,0]
	s_waitcnt vmcnt(2)
	v_pk_mul_f32 v[146:147], v[30:31], s[0:1] op_sel_hi:[1,0]
	v_pk_mul_f32 v[144:145], v[28:29], s[0:1] op_sel_hi:[1,0]
	v_pk_mul_f32 v[150:151], v[22:23], s[0:1] op_sel_hi:[1,0]
	v_pk_mul_f32 v[148:149], v[20:21], s[0:1] op_sel_hi:[1,0]
	v_pk_mul_f32 v[154:155], v[14:15], s[0:1] op_sel_hi:[1,0]
	v_pk_mul_f32 v[152:153], v[12:13], s[0:1] op_sel_hi:[1,0]
	v_pk_mul_f32 v[158:159], v[6:7], s[0:1] op_sel_hi:[1,0]
	v_pk_mul_f32 v[156:157], v[4:5], s[0:1] op_sel_hi:[1,0]
	s_movk_i32 s0, 0x110
	v_mul_lo_u32 v0, v34, s0
	v_add_u32_e32 v0, 0, v0
	v_readlane_b32 s0, v254, 41
	v_add_u32_e32 v176, v0, v160
	v_add_u32_e32 v0, s80, v38
	v_readlane_b32 s1, v254, 42
	v_ashrrev_i32_e32 v1, 31, v0
	v_and_b32_e32 v4, 31, v39
	v_lshl_add_u64 v[2:3], s[0:1], 0, v[32:33]
	v_readlane_b32 s0, v254, 35
	v_lshlrev_b64 v[0:1], 15, v[0:1]
	v_readlane_b32 s1, v254, 36
	v_lshl_add_u64 v[162:163], v[2:3], 0, v[160:161]
	v_lshlrev_b32_e32 v160, 2, v4
	v_lshl_add_u64 v[0:1], s[0:1], 0, v[0:1]
	v_lshl_add_u32 v5, v38, 4, 0
	v_mul_u32_u24_e32 v6, 0x110, v4
	v_lshl_add_u64 v[164:165], v[0:1], 0, v[160:161]
	s_mov_b64 s[0:1], 0x10000
	v_lshl_add_u64 v[166:167], v[164:165], 0, s[0:1]
	v_add_u32_e32 v160, v5, v6
	s_barrier
	s_waitcnt vmcnt(0)
	ds_write_b128 v176, v[112:115]
	ds_write_b128 v176, v[116:119] offset:16
	ds_write_b128 v176, v[120:123] offset:17408
	ds_write_b128 v176, v[124:127] offset:17424
	v_readlane_b32 s4, v254, 7
	v_readlane_b32 s5, v254, 8
	s_mov_b64 s[98:99], 0x4000
	s_load_dwordx2 s[4:5], s[4:5], 0x108
	v_lshl_add_u64 v[232:233], v[230:231], 0, s[98:99]
	v_add_u32_e32 v238, 0, v160
	v_add_u32_e32 v239, 0x8800, v160
	v_add_u32_e32 v240, 0, v176
	v_add_u32_e32 v241, 0x8800, v176
	s_mov_b64 s[2:3], 0x8000
	s_mov_b64 s[100:101], 0x200
	s_add_i32 s8, s6, 1
	s_lshr_b32 s8, s8, 1
	s_waitcnt lgkmcnt(0)
	global_load_dwordx4 v[112:115], v[230:231], off
	global_load_dwordx4 v[116:119], v[230:231], off offset:16
	global_load_dwordx4 v[120:123], v[232:233], off
	global_load_dwordx4 v[124:127], v[232:233], off offset:16
	v_lshl_add_u64 v[230:231], v[230:231], 0, s[2:3]
	v_lshl_add_u64 v[232:233], v[232:233], 0, s[2:3]
	v_lshl_add_u64 v[234:235], s[4:5], 0, v[164:165]
	v_lshl_add_u64 v[236:237], s[4:5], 0, v[166:167]
	s_mov_b32 s99, 1
	s_barrier
	ds_read_b128 v[182:185], v238
	ds_read_b128 v[186:189], v238 offset:32
	ds_read_b128 v[190:193], v238 offset:64
	ds_read_b128 v[194:197], v238 offset:96
	ds_read_b128 v[198:201], v238 offset:128
	ds_read_b128 v[202:205], v238 offset:160
	ds_read_b128 v[206:209], v238 offset:192
	ds_read_b128 v[210:213], v238 offset:224
	s_waitcnt vmcnt(0)
; DI void indexer_unit(unsigned char* ws, LAS unsigned char* lds, int b, int blk, float* scratch, int wave) {
;     ...
;     for (int kt = 0; kt < nk; kt += 2) {
;         IDX_TILE(kt, st0, st1, su0, su1);
;         if (kt + 1 < nk) IDX_TILE(kt + 1, su0, su1, st0, st1);
;     }
.Lidx_loop:
	s_waitcnt vmcnt(19)
	ds_write_b128 v241, v[214:217]
	ds_write_b128 v241, v[218:221] offset:16
	ds_write_b128 v241, v[222:225] offset:17408
	ds_write_b128 v241, v[226:229] offset:17424
	s_waitcnt lgkmcnt(11)
	v_mfma_f32_32x32x16_bf16 v[0:15], v[48:51], v[182:185], 0
	s_waitcnt lgkmcnt(10)
	v_mfma_f32_32x32x16_bf16 v[0:15], v[52:55], v[186:189], v[0:15]
	v_med3_f32 v32, v16, 0, v173
	v_med3_f32 v33, v17, 0, v173
	v_fma_f32 v35, v144, v32, 0
	v_med3_f32 v32, v18, 0, v173
	v_fmac_f32_e32 v35, v145, v33
	s_waitcnt lgkmcnt(9)
	v_mfma_f32_32x32x16_bf16 v[0:15], v[56:59], v[190:193], v[0:15]
	v_med3_f32 v33, v19, 0, v173
	v_fmac_f32_e32 v35, v146, v32
	v_med3_f32 v32, v20, 0, v173
	v_fmac_f32_e32 v35, v147, v33
	v_med3_f32 v33, v21, 0, v173
	s_waitcnt lgkmcnt(8)
	v_mfma_f32_32x32x16_bf16 v[0:15], v[60:63], v[194:197], v[0:15]
	v_fmac_f32_e32 v35, v148, v32
	v_med3_f32 v32, v22, 0, v173
	v_fmac_f32_e32 v35, v149, v33
	v_med3_f32 v33, v23, 0, v173
	v_fmac_f32_e32 v35, v150, v32
	s_waitcnt lgkmcnt(7)
	v_mfma_f32_32x32x16_bf16 v[0:15], v[64:67], v[198:201], v[0:15]
	v_med3_f32 v32, v24, 0, v173
	v_fmac_f32_e32 v35, v151, v33
	v_med3_f32 v33, v25, 0, v173
	v_fmac_f32_e32 v35, v152, v32
	v_med3_f32 v32, v26, 0, v173
	s_waitcnt lgkmcnt(6)
	v_mfma_f32_32x32x16_bf16 v[0:15], v[68:71], v[202:205], v[0:15]
	v_fmac_f32_e32 v35, v153, v33
	v_med3_f32 v33, v27, 0, v173
	v_fmac_f32_e32 v35, v154, v32
	v_med3_f32 v32, v28, 0, v173
	v_fmac_f32_e32 v35, v155, v33
	s_waitcnt lgkmcnt(5)
	v_mfma_f32_32x32x16_bf16 v[0:15], v[72:75], v[206:209], v[0:15]
	v_med3_f32 v33, v29, 0, v173
	v_fmac_f32_e32 v35, v156, v32
	v_med3_f32 v32, v30, 0, v173
	v_fmac_f32_e32 v35, v157, v33
	s_waitcnt lgkmcnt(4)
	v_mfma_f32_32x32x16_bf16 v[0:15], v[76:79], v[210:213], v[0:15]
	v_med3_f32 v33, v31, 0, v173
	v_fmac_f32_e32 v35, v158, v32
	v_fmac_f32_e32 v35, v159, v33
	s_cmp_eq_u32 s99, 1
	s_cbranch_scc1 .Lidx_skipst
	global_store_dword v[236:237], v35, off offset:-384
.Lidx_skipst:
	s_mov_b32 s99, 0
	s_waitcnt lgkmcnt(0)
	global_load_dwordx4 v[214:217], v[230:231], off
	global_load_dwordx4 v[218:221], v[230:231], off offset:16
	global_load_dwordx4 v[222:225], v[232:233], off
	global_load_dwordx4 v[226:229], v[232:233], off offset:16
	v_lshl_add_u64 v[230:231], v[230:231], 0, s[2:3]
	v_lshl_add_u64 v[232:233], v[232:233], 0, s[2:3]
	v_mfma_f32_32x32x16_bf16 v[16:31], v[80:83], v[182:185], 0
	ds_read_b128 v[182:185], v238 offset:8704
	v_mfma_f32_32x32x16_bf16 v[16:31], v[84:87], v[186:189], v[16:31]
	ds_read_b128 v[186:189], v238 offset:8736
	v_med3_f32 v32, v0, 0, v173
	v_med3_f32 v33, v1, 0, v173
	v_fma_f32 v34, v128, v32, 0
	v_med3_f32 v32, v2, 0, v173
	v_fmac_f32_e32 v34, v129, v33
	v_mfma_f32_32x32x16_bf16 v[16:31], v[88:91], v[190:193], v[16:31]
	ds_read_b128 v[190:193], v238 offset:8768
	v_med3_f32 v33, v3, 0, v173
	v_fmac_f32_e32 v34, v130, v32
	v_med3_f32 v32, v4, 0, v173
	v_fmac_f32_e32 v34, v131, v33
	v_med3_f32 v33, v5, 0, v173
	v_mfma_f32_32x32x16_bf16 v[16:31], v[92:95], v[194:197], v[16:31]
	ds_read_b128 v[194:197], v238 offset:8800
	v_fmac_f32_e32 v34, v132, v32
	v_med3_f32 v32, v6, 0, v173
	v_fmac_f32_e32 v34, v133, v33
	v_med3_f32 v33, v7, 0, v173
	v_fmac_f32_e32 v34, v134, v32
	v_mfma_f32_32x32x16_bf16 v[16:31], v[96:99], v[198:201], v[16:31]
	ds_read_b128 v[198:201], v238 offset:8832
	v_med3_f32 v32, v8, 0, v173
	v_fmac_f32_e32 v34, v135, v33
	v_med3_f32 v33, v9, 0, v173
	v_fmac_f32_e32 v34, v136, v32
	v_med3_f32 v32, v10, 0, v173
	v_mfma_f32_32x32x16_bf16 v[16:31], v[100:103], v[202:205], v[16:31]
	ds_read_b128 v[202:205], v238 offset:8864
	v_fmac_f32_e32 v34, v137, v33
	v_med3_f32 v33, v11, 0, v173
	v_fmac_f32_e32 v34, v138, v32
	v_med3_f32 v32, v12, 0, v173
	v_fmac_f32_e32 v34, v139, v33
	v_mfma_f32_32x32x16_bf16 v[16:31], v[104:107], v[206:209], v[16:31]
	ds_read_b128 v[206:209], v238 offset:8896
	v_med3_f32 v33, v13, 0, v173
	v_fmac_f32_e32 v34, v140, v32
	v_med3_f32 v32, v14, 0, v173
	v_fmac_f32_e32 v34, v141, v33
	v_mfma_f32_32x32x16_bf16 v[16:31], v[108:111], v[210:213], v[16:31]
	ds_read_b128 v[210:213], v238 offset:8928
	v_med3_f32 v33, v15, 0, v173
	v_fmac_f32_e32 v34, v142, v32
	v_fmac_f32_e32 v34, v143, v33
	global_store_dword v[234:235], v34, off offset:-256
	s_waitcnt lgkmcnt(7)
	v_mfma_f32_32x32x16_bf16 v[0:15], v[48:51], v[182:185], 0
	s_waitcnt lgkmcnt(6)
	v_mfma_f32_32x32x16_bf16 v[0:15], v[52:55], v[186:189], v[0:15]
	s_nop 2
	v_med3_f32 v32, v16, 0, v173
	v_med3_f32 v33, v17, 0, v173
	v_fma_f32 v35, v144, v32, 0
	v_med3_f32 v32, v18, 0, v173
	v_fmac_f32_e32 v35, v145, v33
	s_waitcnt lgkmcnt(5)
	v_mfma_f32_32x32x16_bf16 v[0:15], v[56:59], v[190:193], v[0:15]
	v_med3_f32 v33, v19, 0, v173
	v_fmac_f32_e32 v35, v146, v32
	v_med3_f32 v32, v20, 0, v173
	v_fmac_f32_e32 v35, v147, v33
	v_med3_f32 v33, v21, 0, v173
	s_waitcnt lgkmcnt(4)
	v_mfma_f32_32x32x16_bf16 v[0:15], v[60:63], v[194:197], v[0:15]
	v_fmac_f32_e32 v35, v148, v32
	v_med3_f32 v32, v22, 0, v173
	v_fmac_f32_e32 v35, v149, v33
	v_med3_f32 v33, v23, 0, v173
	v_fmac_f32_e32 v35, v150, v32
	s_waitcnt lgkmcnt(3)
	v_mfma_f32_32x32x16_bf16 v[0:15], v[64:67], v[198:201], v[0:15]
	v_med3_f32 v32, v24, 0, v173
	v_fmac_f32_e32 v35, v151, v33
	v_med3_f32 v33, v25, 0, v173
	v_fmac_f32_e32 v35, v152, v32
	v_med3_f32 v32, v26, 0, v173
	s_waitcnt lgkmcnt(2)
	v_mfma_f32_32x32x16_bf16 v[0:15], v[68:71], v[202:205], v[0:15]
	v_fmac_f32_e32 v35, v153, v33
	v_med3_f32 v33, v27, 0, v173
	v_fmac_f32_e32 v35, v154, v32
	v_med3_f32 v32, v28, 0, v173
	v_fmac_f32_e32 v35, v155, v33
	s_waitcnt lgkmcnt(1)
; DI void indexer_unit(unsigned char* ws, LAS unsigned char* lds, int b, int blk, float* scratch, int wave) {
;     ...
;     for (int kt = 0; kt < nk; kt += 2) {
;         IDX_TILE(kt, st0, st1, su0, su1);
;         if (kt + 1 < nk) IDX_TILE(kt + 1, su0, su1, st0, st1);
;     }
	v_mfma_f32_32x32x16_bf16 v[0:15], v[72:75], v[206:209], v[0:15]
	v_med3_f32 v33, v29, 0, v173
	v_fmac_f32_e32 v35, v156, v32
	v_med3_f32 v32, v30, 0, v173
	v_fmac_f32_e32 v35, v157, v33
	s_waitcnt lgkmcnt(0)
	v_mfma_f32_32x32x16_bf16 v[0:15], v[76:79], v[210:213], v[0:15]
	v_med3_f32 v33, v31, 0, v173
	v_fmac_f32_e32 v35, v158, v32
	v_fmac_f32_e32 v35, v159, v33
	global_store_dword v[236:237], v35, off offset:-256
	v_mfma_f32_32x32x16_bf16 v[16:31], v[80:83], v[182:185], 0
	ds_read_b128 v[182:185], v238 offset:17408
	v_mfma_f32_32x32x16_bf16 v[16:31], v[84:87], v[186:189], v[16:31]
	ds_read_b128 v[186:189], v238 offset:17440
	s_nop 3
	v_med3_f32 v32, v0, 0, v173
	v_med3_f32 v33, v1, 0, v173
	v_fma_f32 v34, v128, v32, 0
	v_med3_f32 v32, v2, 0, v173
	v_fmac_f32_e32 v34, v129, v33
	v_mfma_f32_32x32x16_bf16 v[16:31], v[88:91], v[190:193], v[16:31]
	ds_read_b128 v[190:193], v238 offset:17472
	v_med3_f32 v33, v3, 0, v173
	v_fmac_f32_e32 v34, v130, v32
	v_med3_f32 v32, v4, 0, v173
	v_fmac_f32_e32 v34, v131, v33
	v_med3_f32 v33, v5, 0, v173
	v_mfma_f32_32x32x16_bf16 v[16:31], v[92:95], v[194:197], v[16:31]
	ds_read_b128 v[194:197], v238 offset:17504
	v_fmac_f32_e32 v34, v132, v32
	v_med3_f32 v32, v6, 0, v173
	v_fmac_f32_e32 v34, v133, v33
	v_med3_f32 v33, v7, 0, v173
	v_fmac_f32_e32 v34, v134, v32
	v_mfma_f32_32x32x16_bf16 v[16:31], v[96:99], v[198:201], v[16:31]
	ds_read_b128 v[198:201], v238 offset:17536
	v_med3_f32 v32, v8, 0, v173
	v_fmac_f32_e32 v34, v135, v33
	v_med3_f32 v33, v9, 0, v173
	v_fmac_f32_e32 v34, v136, v32
	v_med3_f32 v32, v10, 0, v173
	v_mfma_f32_32x32x16_bf16 v[16:31], v[100:103], v[202:205], v[16:31]
	ds_read_b128 v[202:205], v238 offset:17568
	v_fmac_f32_e32 v34, v137, v33
	v_med3_f32 v33, v11, 0, v173
	v_fmac_f32_e32 v34, v138, v32
	v_med3_f32 v32, v12, 0, v173
	v_fmac_f32_e32 v34, v139, v33
	v_mfma_f32_32x32x16_bf16 v[16:31], v[104:107], v[206:209], v[16:31]
	ds_read_b128 v[206:209], v238 offset:17600
	v_med3_f32 v33, v13, 0, v173
	v_fmac_f32_e32 v34, v140, v32
	v_med3_f32 v32, v14, 0, v173
	v_fmac_f32_e32 v34, v141, v33
	v_mfma_f32_32x32x16_bf16 v[16:31], v[108:111], v[210:213], v[16:31]
	ds_read_b128 v[210:213], v238 offset:17632
	v_med3_f32 v33, v15, 0, v173
	v_fmac_f32_e32 v34, v142, v32
	v_fmac_f32_e32 v34, v143, v33
	global_store_dword v[234:235], v34, off offset:-128
	s_waitcnt lgkmcnt(7)
	v_mfma_f32_32x32x16_bf16 v[0:15], v[48:51], v[182:185], 0
	s_waitcnt lgkmcnt(6)
	v_mfma_f32_32x32x16_bf16 v[0:15], v[52:55], v[186:189], v[0:15]
	s_nop 2
	v_med3_f32 v32, v16, 0, v173
	v_med3_f32 v33, v17, 0, v173
	v_fma_f32 v35, v144, v32, 0
	v_med3_f32 v32, v18, 0, v173
	v_fmac_f32_e32 v35, v145, v33
	s_waitcnt lgkmcnt(5)
	v_mfma_f32_32x32x16_bf16 v[0:15], v[56:59], v[190:193], v[0:15]
	v_med3_f32 v33, v19, 0, v173
	v_fmac_f32_e32 v35, v146, v32
	v_med3_f32 v32, v20, 0, v173
	v_fmac_f32_e32 v35, v147, v33
	v_med3_f32 v33, v21, 0, v173
	s_waitcnt lgkmcnt(4)
	v_mfma_f32_32x32x16_bf16 v[0:15], v[60:63], v[194:197], v[0:15]
	v_fmac_f32_e32 v35, v148, v32
	v_med3_f32 v32, v22, 0, v173
	v_fmac_f32_e32 v35, v149, v33
	v_med3_f32 v33, v23, 0, v173
	v_fmac_f32_e32 v35, v150, v32
	s_waitcnt lgkmcnt(3)
	v_mfma_f32_32x32x16_bf16 v[0:15], v[64:67], v[198:201], v[0:15]
	v_med3_f32 v32, v24, 0, v173
	v_fmac_f32_e32 v35, v151, v33
	v_med3_f32 v33, v25, 0, v173
	v_fmac_f32_e32 v35, v152, v32
	v_med3_f32 v32, v26, 0, v173
	s_waitcnt lgkmcnt(2)
	v_mfma_f32_32x32x16_bf16 v[0:15], v[68:71], v[202:205], v[0:15]
	v_fmac_f32_e32 v35, v153, v33
	v_med3_f32 v33, v27, 0, v173
	v_fmac_f32_e32 v35, v154, v32
	v_med3_f32 v32, v28, 0, v173
	v_fmac_f32_e32 v35, v155, v33
	s_waitcnt lgkmcnt(1)
	v_mfma_f32_32x32x16_bf16 v[0:15], v[72:75], v[206:209], v[0:15]
	v_med3_f32 v33, v29, 0, v173
	v_fmac_f32_e32 v35, v156, v32
	v_med3_f32 v32, v30, 0, v173
	v_fmac_f32_e32 v35, v157, v33
	s_waitcnt lgkmcnt(0)
	v_mfma_f32_32x32x16_bf16 v[0:15], v[76:79], v[210:213], v[0:15]
	v_med3_f32 v33, v31, 0, v173
	v_fmac_f32_e32 v35, v158, v32
	v_fmac_f32_e32 v35, v159, v33
	global_store_dword v[236:237], v35, off offset:-128
	v_mfma_f32_32x32x16_bf16 v[16:31], v[80:83], v[182:185], 0
	ds_read_b128 v[182:185], v238 offset:26112
	v_mfma_f32_32x32x16_bf16 v[16:31], v[84:87], v[186:189], v[16:31]
	ds_read_b128 v[186:189], v238 offset:26144
	s_nop 3
	v_med3_f32 v32, v0, 0, v173
	v_med3_f32 v33, v1, 0, v173
	v_fma_f32 v34, v128, v32, 0
	v_med3_f32 v32, v2, 0, v173
	v_fmac_f32_e32 v34, v129, v33
	v_mfma_f32_32x32x16_bf16 v[16:31], v[88:91], v[190:193], v[16:31]
	ds_read_b128 v[190:193], v238 offset:26176
	v_med3_f32 v33, v3, 0, v173
	v_fmac_f32_e32 v34, v130, v32
	v_med3_f32 v32, v4, 0, v173
	v_fmac_f32_e32 v34, v131, v33
	v_med3_f32 v33, v5, 0, v173
	v_mfma_f32_32x32x16_bf16 v[16:31], v[92:95], v[194:197], v[16:31]
	ds_read_b128 v[194:197], v238 offset:26208
	v_fmac_f32_e32 v34, v132, v32
	v_med3_f32 v32, v6, 0, v173
	v_fmac_f32_e32 v34, v133, v33
	v_med3_f32 v33, v7, 0, v173
	v_fmac_f32_e32 v34, v134, v32
	v_mfma_f32_32x32x16_bf16 v[16:31], v[96:99], v[198:201], v[16:31]
	ds_read_b128 v[198:201], v238 offset:26240
	v_med3_f32 v32, v8, 0, v173
	v_fmac_f32_e32 v34, v135, v33
	v_med3_f32 v33, v9, 0, v173
	v_fmac_f32_e32 v34, v136, v32
	v_med3_f32 v32, v10, 0, v173
	v_mfma_f32_32x32x16_bf16 v[16:31], v[100:103], v[202:205], v[16:31]
	ds_read_b128 v[202:205], v238 offset:26272
	v_fmac_f32_e32 v34, v137, v33
	v_med3_f32 v33, v11, 0, v173
	v_fmac_f32_e32 v34, v138, v32
	v_med3_f32 v32, v12, 0, v173
	v_fmac_f32_e32 v34, v139, v33
	v_mfma_f32_32x32x16_bf16 v[16:31], v[104:107], v[206:209], v[16:31]
	ds_read_b128 v[206:209], v238 offset:26304
	v_med3_f32 v33, v13, 0, v173
	v_fmac_f32_e32 v34, v140, v32
	v_med3_f32 v32, v14, 0, v173
	v_fmac_f32_e32 v34, v141, v33
	v_mfma_f32_32x32x16_bf16 v[16:31], v[108:111], v[210:213], v[16:31]
	ds_read_b128 v[210:213], v238 offset:26336
	v_med3_f32 v33, v15, 0, v173
	v_fmac_f32_e32 v34, v142, v32
	v_fmac_f32_e32 v34, v143, v33
	global_store_dword v[234:235], v34, off offset:0
	s_waitcnt lgkmcnt(7)
; DI void indexer_unit(unsigned char* ws, LAS unsigned char* lds, int b, int blk, float* scratch, int wave) {
;     ...
;     for (int kt = 0; kt < nk; kt += 2) {
;         IDX_TILE(kt, st0, st1, su0, su1);
;         if (kt + 1 < nk) IDX_TILE(kt + 1, su0, su1, st0, st1);
;     }
	v_mfma_f32_32x32x16_bf16 v[0:15], v[48:51], v[182:185], 0
	s_waitcnt lgkmcnt(6)
	v_mfma_f32_32x32x16_bf16 v[0:15], v[52:55], v[186:189], v[0:15]
	s_nop 2
	v_med3_f32 v32, v16, 0, v173
	v_med3_f32 v33, v17, 0, v173
	v_fma_f32 v35, v144, v32, 0
	v_med3_f32 v32, v18, 0, v173
	v_fmac_f32_e32 v35, v145, v33
	s_waitcnt lgkmcnt(5)
	v_mfma_f32_32x32x16_bf16 v[0:15], v[56:59], v[190:193], v[0:15]
	v_med3_f32 v33, v19, 0, v173
	v_fmac_f32_e32 v35, v146, v32
	v_med3_f32 v32, v20, 0, v173
	v_fmac_f32_e32 v35, v147, v33
	v_med3_f32 v33, v21, 0, v173
	s_waitcnt lgkmcnt(4)
	v_mfma_f32_32x32x16_bf16 v[0:15], v[60:63], v[194:197], v[0:15]
	v_fmac_f32_e32 v35, v148, v32
	v_med3_f32 v32, v22, 0, v173
	v_fmac_f32_e32 v35, v149, v33
	v_med3_f32 v33, v23, 0, v173
	v_fmac_f32_e32 v35, v150, v32
	s_waitcnt lgkmcnt(3)
	v_mfma_f32_32x32x16_bf16 v[0:15], v[64:67], v[198:201], v[0:15]
	v_med3_f32 v32, v24, 0, v173
	v_fmac_f32_e32 v35, v151, v33
	v_med3_f32 v33, v25, 0, v173
	v_fmac_f32_e32 v35, v152, v32
	v_med3_f32 v32, v26, 0, v173
	s_waitcnt lgkmcnt(2)
	v_mfma_f32_32x32x16_bf16 v[0:15], v[68:71], v[202:205], v[0:15]
	v_fmac_f32_e32 v35, v153, v33
	v_med3_f32 v33, v27, 0, v173
	v_fmac_f32_e32 v35, v154, v32
	v_med3_f32 v32, v28, 0, v173
	v_fmac_f32_e32 v35, v155, v33
	s_waitcnt lgkmcnt(1)
	v_mfma_f32_32x32x16_bf16 v[0:15], v[72:75], v[206:209], v[0:15]
	v_med3_f32 v33, v29, 0, v173
	v_fmac_f32_e32 v35, v156, v32
	v_med3_f32 v32, v30, 0, v173
	v_fmac_f32_e32 v35, v157, v33
	s_waitcnt lgkmcnt(0)
	v_mfma_f32_32x32x16_bf16 v[0:15], v[76:79], v[210:213], v[0:15]
	v_med3_f32 v33, v31, 0, v173
	v_fmac_f32_e32 v35, v158, v32
	v_fmac_f32_e32 v35, v159, v33
	global_store_dword v[236:237], v35, off offset:0
	s_barrier
	v_mfma_f32_32x32x16_bf16 v[16:31], v[80:83], v[182:185], 0
	ds_read_b128 v[182:185], v239
	v_mfma_f32_32x32x16_bf16 v[16:31], v[84:87], v[186:189], v[16:31]
	ds_read_b128 v[186:189], v239 offset:32
	s_nop 2
	v_med3_f32 v32, v0, 0, v173
	v_med3_f32 v33, v1, 0, v173
	v_fma_f32 v34, v128, v32, 0
	v_med3_f32 v32, v2, 0, v173
	v_fmac_f32_e32 v34, v129, v33
	v_mfma_f32_32x32x16_bf16 v[16:31], v[88:91], v[190:193], v[16:31]
	ds_read_b128 v[190:193], v239 offset:64
	v_med3_f32 v33, v3, 0, v173
	v_fmac_f32_e32 v34, v130, v32
	v_med3_f32 v32, v4, 0, v173
	v_fmac_f32_e32 v34, v131, v33
	v_med3_f32 v33, v5, 0, v173
	v_mfma_f32_32x32x16_bf16 v[16:31], v[92:95], v[194:197], v[16:31]
	ds_read_b128 v[194:197], v239 offset:96
	v_fmac_f32_e32 v34, v132, v32
	v_med3_f32 v32, v6, 0, v173
	v_fmac_f32_e32 v34, v133, v33
	v_med3_f32 v33, v7, 0, v173
	v_fmac_f32_e32 v34, v134, v32
	v_mfma_f32_32x32x16_bf16 v[16:31], v[96:99], v[198:201], v[16:31]
	ds_read_b128 v[198:201], v239 offset:128
	v_med3_f32 v32, v8, 0, v173
	v_fmac_f32_e32 v34, v135, v33
	v_med3_f32 v33, v9, 0, v173
	v_fmac_f32_e32 v34, v136, v32
	v_med3_f32 v32, v10, 0, v173
	v_mfma_f32_32x32x16_bf16 v[16:31], v[100:103], v[202:205], v[16:31]
	ds_read_b128 v[202:205], v239 offset:160
	v_fmac_f32_e32 v34, v137, v33
	v_med3_f32 v33, v11, 0, v173
	v_fmac_f32_e32 v34, v138, v32
	v_med3_f32 v32, v12, 0, v173
	v_fmac_f32_e32 v34, v139, v33
	v_mfma_f32_32x32x16_bf16 v[16:31], v[104:107], v[206:209], v[16:31]
	ds_read_b128 v[206:209], v239 offset:192
	v_med3_f32 v33, v13, 0, v173
	v_fmac_f32_e32 v34, v140, v32
	v_med3_f32 v32, v14, 0, v173
	v_fmac_f32_e32 v34, v141, v33
	v_mfma_f32_32x32x16_bf16 v[16:31], v[108:111], v[210:213], v[16:31]
	ds_read_b128 v[210:213], v239 offset:224
	v_med3_f32 v33, v15, 0, v173
	v_fmac_f32_e32 v34, v142, v32
	v_fmac_f32_e32 v34, v143, v33
	global_store_dword v[234:235], v34, off offset:128
	v_lshl_add_u64 v[234:235], v[234:235], 0, s[100:101]
	v_lshl_add_u64 v[236:237], v[236:237], 0, s[100:101]
	s_add_i32 s8, s8, -1
	s_cmp_eq_u32 s8, 0
	s_cbranch_scc1 .Lidx_done
	s_waitcnt vmcnt(19)
	ds_write_b128 v240, v[112:115]
	ds_write_b128 v240, v[116:119] offset:16
	ds_write_b128 v240, v[120:123] offset:17408
	ds_write_b128 v240, v[124:127] offset:17424
	s_waitcnt lgkmcnt(11)
	v_mfma_f32_32x32x16_bf16 v[0:15], v[48:51], v[182:185], 0
	s_waitcnt lgkmcnt(10)
	v_mfma_f32_32x32x16_bf16 v[0:15], v[52:55], v[186:189], v[0:15]
	v_med3_f32 v32, v16, 0, v173
	v_med3_f32 v33, v17, 0, v173
	v_fma_f32 v35, v144, v32, 0
	v_med3_f32 v32, v18, 0, v173
	v_fmac_f32_e32 v35, v145, v33
	s_waitcnt lgkmcnt(9)
	v_mfma_f32_32x32x16_bf16 v[0:15], v[56:59], v[190:193], v[0:15]
	v_med3_f32 v33, v19, 0, v173
	v_fmac_f32_e32 v35, v146, v32
	v_med3_f32 v32, v20, 0, v173
	v_fmac_f32_e32 v35, v147, v33
	v_med3_f32 v33, v21, 0, v173
	s_waitcnt lgkmcnt(8)
	v_mfma_f32_32x32x16_bf16 v[0:15], v[60:63], v[194:197], v[0:15]
	v_fmac_f32_e32 v35, v148, v32
	v_med3_f32 v32, v22, 0, v173
	v_fmac_f32_e32 v35, v149, v33
	v_med3_f32 v33, v23, 0, v173
	v_fmac_f32_e32 v35, v150, v32
	s_waitcnt lgkmcnt(7)
	v_mfma_f32_32x32x16_bf16 v[0:15], v[64:67], v[198:201], v[0:15]
	v_med3_f32 v32, v24, 0, v173
	v_fmac_f32_e32 v35, v151, v33
	v_med3_f32 v33, v25, 0, v173
	v_fmac_f32_e32 v35, v152, v32
	v_med3_f32 v32, v26, 0, v173
	s_waitcnt lgkmcnt(6)
	v_mfma_f32_32x32x16_bf16 v[0:15], v[68:71], v[202:205], v[0:15]
	v_fmac_f32_e32 v35, v153, v33
	v_med3_f32 v33, v27, 0, v173
	v_fmac_f32_e32 v35, v154, v32
	v_med3_f32 v32, v28, 0, v173
	v_fmac_f32_e32 v35, v155, v33
	s_waitcnt lgkmcnt(5)
	v_mfma_f32_32x32x16_bf16 v[0:15], v[72:75], v[206:209], v[0:15]
	v_med3_f32 v33, v29, 0, v173
	v_fmac_f32_e32 v35, v156, v32
	v_med3_f32 v32, v30, 0, v173
	v_fmac_f32_e32 v35, v157, v33
	s_waitcnt lgkmcnt(4)
	v_mfma_f32_32x32x16_bf16 v[0:15], v[76:79], v[210:213], v[0:15]
	v_med3_f32 v33, v31, 0, v173
	v_fmac_f32_e32 v35, v158, v32
	v_fmac_f32_e32 v35, v159, v33
	global_store_dword v[236:237], v35, off offset:-384
	s_waitcnt lgkmcnt(0)
; DI void indexer_unit(unsigned char* ws, LAS unsigned char* lds, int b, int blk, float* scratch, int wave) {
;     ...
;     for (int kt = 0; kt < nk; kt += 2) {
;         IDX_TILE(kt, st0, st1, su0, su1);
;         if (kt + 1 < nk) IDX_TILE(kt + 1, su0, su1, st0, st1);
;     }
	global_load_dwordx4 v[112:115], v[230:231], off
	global_load_dwordx4 v[116:119], v[230:231], off offset:16
	global_load_dwordx4 v[120:123], v[232:233], off
	global_load_dwordx4 v[124:127], v[232:233], off offset:16
	v_lshl_add_u64 v[230:231], v[230:231], 0, s[2:3]
	v_lshl_add_u64 v[232:233], v[232:233], 0, s[2:3]
	v_mfma_f32_32x32x16_bf16 v[16:31], v[80:83], v[182:185], 0
	ds_read_b128 v[182:185], v239 offset:8704
	v_mfma_f32_32x32x16_bf16 v[16:31], v[84:87], v[186:189], v[16:31]
	ds_read_b128 v[186:189], v239 offset:8736
	v_med3_f32 v32, v0, 0, v173
	v_med3_f32 v33, v1, 0, v173
	v_fma_f32 v34, v128, v32, 0
	v_med3_f32 v32, v2, 0, v173
	v_fmac_f32_e32 v34, v129, v33
	v_mfma_f32_32x32x16_bf16 v[16:31], v[88:91], v[190:193], v[16:31]
	ds_read_b128 v[190:193], v239 offset:8768
	v_med3_f32 v33, v3, 0, v173
	v_fmac_f32_e32 v34, v130, v32
	v_med3_f32 v32, v4, 0, v173
	v_fmac_f32_e32 v34, v131, v33
	v_med3_f32 v33, v5, 0, v173
	v_mfma_f32_32x32x16_bf16 v[16:31], v[92:95], v[194:197], v[16:31]
	ds_read_b128 v[194:197], v239 offset:8800
	v_fmac_f32_e32 v34, v132, v32
	v_med3_f32 v32, v6, 0, v173
	v_fmac_f32_e32 v34, v133, v33
	v_med3_f32 v33, v7, 0, v173
	v_fmac_f32_e32 v34, v134, v32
	v_mfma_f32_32x32x16_bf16 v[16:31], v[96:99], v[198:201], v[16:31]
	ds_read_b128 v[198:201], v239 offset:8832
	v_med3_f32 v32, v8, 0, v173
	v_fmac_f32_e32 v34, v135, v33
	v_med3_f32 v33, v9, 0, v173
	v_fmac_f32_e32 v34, v136, v32
	v_med3_f32 v32, v10, 0, v173
	v_mfma_f32_32x32x16_bf16 v[16:31], v[100:103], v[202:205], v[16:31]
	ds_read_b128 v[202:205], v239 offset:8864
	v_fmac_f32_e32 v34, v137, v33
	v_med3_f32 v33, v11, 0, v173
	v_fmac_f32_e32 v34, v138, v32
	v_med3_f32 v32, v12, 0, v173
	v_fmac_f32_e32 v34, v139, v33
	v_mfma_f32_32x32x16_bf16 v[16:31], v[104:107], v[206:209], v[16:31]
	ds_read_b128 v[206:209], v239 offset:8896
	v_med3_f32 v33, v13, 0, v173
	v_fmac_f32_e32 v34, v140, v32
	v_med3_f32 v32, v14, 0, v173
	v_fmac_f32_e32 v34, v141, v33
	v_mfma_f32_32x32x16_bf16 v[16:31], v[108:111], v[210:213], v[16:31]
	ds_read_b128 v[210:213], v239 offset:8928
	v_med3_f32 v33, v15, 0, v173
	v_fmac_f32_e32 v34, v142, v32
	v_fmac_f32_e32 v34, v143, v33
	global_store_dword v[234:235], v34, off offset:-256
	s_waitcnt lgkmcnt(7)
	v_mfma_f32_32x32x16_bf16 v[0:15], v[48:51], v[182:185], 0
	s_waitcnt lgkmcnt(6)
	v_mfma_f32_32x32x16_bf16 v[0:15], v[52:55], v[186:189], v[0:15]
	s_nop 2
	v_med3_f32 v32, v16, 0, v173
	v_med3_f32 v33, v17, 0, v173
	v_fma_f32 v35, v144, v32, 0
	v_med3_f32 v32, v18, 0, v173
	v_fmac_f32_e32 v35, v145, v33
	s_waitcnt lgkmcnt(5)
	v_mfma_f32_32x32x16_bf16 v[0:15], v[56:59], v[190:193], v[0:15]
	v_med3_f32 v33, v19, 0, v173
	v_fmac_f32_e32 v35, v146, v32
	v_med3_f32 v32, v20, 0, v173
	v_fmac_f32_e32 v35, v147, v33
	v_med3_f32 v33, v21, 0, v173
	s_waitcnt lgkmcnt(4)
	v_mfma_f32_32x32x16_bf16 v[0:15], v[60:63], v[194:197], v[0:15]
	v_fmac_f32_e32 v35, v148, v32
	v_med3_f32 v32, v22, 0, v173
	v_fmac_f32_e32 v35, v149, v33
	v_med3_f32 v33, v23, 0, v173
	v_fmac_f32_e32 v35, v150, v32
	s_waitcnt lgkmcnt(3)
	v_mfma_f32_32x32x16_bf16 v[0:15], v[64:67], v[198:201], v[0:15]
	v_med3_f32 v32, v24, 0, v173
	v_fmac_f32_e32 v35, v151, v33
	v_med3_f32 v33, v25, 0, v173
	v_fmac_f32_e32 v35, v152, v32
	v_med3_f32 v32, v26, 0, v173
	s_waitcnt lgkmcnt(2)
	v_mfma_f32_32x32x16_bf16 v[0:15], v[68:71], v[202:205], v[0:15]
	v_fmac_f32_e32 v35, v153, v33
	v_med3_f32 v33, v27, 0, v173
	v_fmac_f32_e32 v35, v154, v32
	v_med3_f32 v32, v28, 0, v173
	v_fmac_f32_e32 v35, v155, v33
	s_waitcnt lgkmcnt(1)
	v_mfma_f32_32x32x16_bf16 v[0:15], v[72:75], v[206:209], v[0:15]
	v_med3_f32 v33, v29, 0, v173
	v_fmac_f32_e32 v35, v156, v32
	v_med3_f32 v32, v30, 0, v173
	v_fmac_f32_e32 v35, v157, v33
	s_waitcnt lgkmcnt(0)
	v_mfma_f32_32x32x16_bf16 v[0:15], v[76:79], v[210:213], v[0:15]
	v_med3_f32 v33, v31, 0, v173
	v_fmac_f32_e32 v35, v158, v32
	v_fmac_f32_e32 v35, v159, v33
	global_store_dword v[236:237], v35, off offset:-256
	v_mfma_f32_32x32x16_bf16 v[16:31], v[80:83], v[182:185], 0
	ds_read_b128 v[182:185], v239 offset:17408
	v_mfma_f32_32x32x16_bf16 v[16:31], v[84:87], v[186:189], v[16:31]
	ds_read_b128 v[186:189], v239 offset:17440
	s_nop 3
	v_med3_f32 v32, v0, 0, v173
	v_med3_f32 v33, v1, 0, v173
	v_fma_f32 v34, v128, v32, 0
	v_med3_f32 v32, v2, 0, v173
	v_fmac_f32_e32 v34, v129, v33
	v_mfma_f32_32x32x16_bf16 v[16:31], v[88:91], v[190:193], v[16:31]
	ds_read_b128 v[190:193], v239 offset:17472
	v_med3_f32 v33, v3, 0, v173
	v_fmac_f32_e32 v34, v130, v32
	v_med3_f32 v32, v4, 0, v173
	v_fmac_f32_e32 v34, v131, v33
	v_med3_f32 v33, v5, 0, v173
	v_mfma_f32_32x32x16_bf16 v[16:31], v[92:95], v[194:197], v[16:31]
	ds_read_b128 v[194:197], v239 offset:17504
	v_fmac_f32_e32 v34, v132, v32
	v_med3_f32 v32, v6, 0, v173
	v_fmac_f32_e32 v34, v133, v33
	v_med3_f32 v33, v7, 0, v173
	v_fmac_f32_e32 v34, v134, v32
	v_mfma_f32_32x32x16_bf16 v[16:31], v[96:99], v[198:201], v[16:31]
	ds_read_b128 v[198:201], v239 offset:17536
	v_med3_f32 v32, v8, 0, v173
	v_fmac_f32_e32 v34, v135, v33
	v_med3_f32 v33, v9, 0, v173
	v_fmac_f32_e32 v34, v136, v32
	v_med3_f32 v32, v10, 0, v173
	v_mfma_f32_32x32x16_bf16 v[16:31], v[100:103], v[202:205], v[16:31]
	ds_read_b128 v[202:205], v239 offset:17568
	v_fmac_f32_e32 v34, v137, v33
	v_med3_f32 v33, v11, 0, v173
	v_fmac_f32_e32 v34, v138, v32
	v_med3_f32 v32, v12, 0, v173
	v_fmac_f32_e32 v34, v139, v33
	v_mfma_f32_32x32x16_bf16 v[16:31], v[104:107], v[206:209], v[16:31]
	ds_read_b128 v[206:209], v239 offset:17600
	v_med3_f32 v33, v13, 0, v173
	v_fmac_f32_e32 v34, v140, v32
	v_med3_f32 v32, v14, 0, v173
	v_fmac_f32_e32 v34, v141, v33
	v_mfma_f32_32x32x16_bf16 v[16:31], v[108:111], v[210:213], v[16:31]
	ds_read_b128 v[210:213], v239 offset:17632
	v_med3_f32 v33, v15, 0, v173
	v_fmac_f32_e32 v34, v142, v32
	v_fmac_f32_e32 v34, v143, v33
	global_store_dword v[234:235], v34, off offset:-128
	s_waitcnt lgkmcnt(7)
; DI void indexer_unit(unsigned char* ws, LAS unsigned char* lds, int b, int blk, float* scratch, int wave) {
;     ...
;     for (int kt = 0; kt < nk; kt += 2) {
;         IDX_TILE(kt, st0, st1, su0, su1);
;         if (kt + 1 < nk) IDX_TILE(kt + 1, su0, su1, st0, st1);
;     }
	v_mfma_f32_32x32x16_bf16 v[0:15], v[48:51], v[182:185], 0
	s_waitcnt lgkmcnt(6)
	v_mfma_f32_32x32x16_bf16 v[0:15], v[52:55], v[186:189], v[0:15]
	s_nop 2
	v_med3_f32 v32, v16, 0, v173
	v_med3_f32 v33, v17, 0, v173
	v_fma_f32 v35, v144, v32, 0
	v_med3_f32 v32, v18, 0, v173
	v_fmac_f32_e32 v35, v145, v33
	s_waitcnt lgkmcnt(5)
	v_mfma_f32_32x32x16_bf16 v[0:15], v[56:59], v[190:193], v[0:15]
	v_med3_f32 v33, v19, 0, v173
	v_fmac_f32_e32 v35, v146, v32
	v_med3_f32 v32, v20, 0, v173
	v_fmac_f32_e32 v35, v147, v33
	v_med3_f32 v33, v21, 0, v173
	s_waitcnt lgkmcnt(4)
	v_mfma_f32_32x32x16_bf16 v[0:15], v[60:63], v[194:197], v[0:15]
	v_fmac_f32_e32 v35, v148, v32
	v_med3_f32 v32, v22, 0, v173
	v_fmac_f32_e32 v35, v149, v33
	v_med3_f32 v33, v23, 0, v173
	v_fmac_f32_e32 v35, v150, v32
	s_waitcnt lgkmcnt(3)
	v_mfma_f32_32x32x16_bf16 v[0:15], v[64:67], v[198:201], v[0:15]
	v_med3_f32 v32, v24, 0, v173
	v_fmac_f32_e32 v35, v151, v33
	v_med3_f32 v33, v25, 0, v173
	v_fmac_f32_e32 v35, v152, v32
	v_med3_f32 v32, v26, 0, v173
	s_waitcnt lgkmcnt(2)
	v_mfma_f32_32x32x16_bf16 v[0:15], v[68:71], v[202:205], v[0:15]
	v_fmac_f32_e32 v35, v153, v33
	v_med3_f32 v33, v27, 0, v173
	v_fmac_f32_e32 v35, v154, v32
	v_med3_f32 v32, v28, 0, v173
	v_fmac_f32_e32 v35, v155, v33
	s_waitcnt lgkmcnt(1)
	v_mfma_f32_32x32x16_bf16 v[0:15], v[72:75], v[206:209], v[0:15]
	v_med3_f32 v33, v29, 0, v173
	v_fmac_f32_e32 v35, v156, v32
	v_med3_f32 v32, v30, 0, v173
	v_fmac_f32_e32 v35, v157, v33
	s_waitcnt lgkmcnt(0)
	v_mfma_f32_32x32x16_bf16 v[0:15], v[76:79], v[210:213], v[0:15]
	v_med3_f32 v33, v31, 0, v173
	v_fmac_f32_e32 v35, v158, v32
	v_fmac_f32_e32 v35, v159, v33
	global_store_dword v[236:237], v35, off offset:-128
	v_mfma_f32_32x32x16_bf16 v[16:31], v[80:83], v[182:185], 0
	ds_read_b128 v[182:185], v239 offset:26112
	v_mfma_f32_32x32x16_bf16 v[16:31], v[84:87], v[186:189], v[16:31]
	ds_read_b128 v[186:189], v239 offset:26144
	s_nop 3
	v_med3_f32 v32, v0, 0, v173
	v_med3_f32 v33, v1, 0, v173
	v_fma_f32 v34, v128, v32, 0
	v_med3_f32 v32, v2, 0, v173
	v_fmac_f32_e32 v34, v129, v33
	v_mfma_f32_32x32x16_bf16 v[16:31], v[88:91], v[190:193], v[16:31]
	ds_read_b128 v[190:193], v239 offset:26176
	v_med3_f32 v33, v3, 0, v173
	v_fmac_f32_e32 v34, v130, v32
	v_med3_f32 v32, v4, 0, v173
	v_fmac_f32_e32 v34, v131, v33
	v_med3_f32 v33, v5, 0, v173
	v_mfma_f32_32x32x16_bf16 v[16:31], v[92:95], v[194:197], v[16:31]
	ds_read_b128 v[194:197], v239 offset:26208
	v_fmac_f32_e32 v34, v132, v32
	v_med3_f32 v32, v6, 0, v173
	v_fmac_f32_e32 v34, v133, v33
	v_med3_f32 v33, v7, 0, v173
	v_fmac_f32_e32 v34, v134, v32
	v_mfma_f32_32x32x16_bf16 v[16:31], v[96:99], v[198:201], v[16:31]
	ds_read_b128 v[198:201], v239 offset:26240
	v_med3_f32 v32, v8, 0, v173
	v_fmac_f32_e32 v34, v135, v33
	v_med3_f32 v33, v9, 0, v173
	v_fmac_f32_e32 v34, v136, v32
	v_med3_f32 v32, v10, 0, v173
	v_mfma_f32_32x32x16_bf16 v[16:31], v[100:103], v[202:205], v[16:31]
	ds_read_b128 v[202:205], v239 offset:26272
	v_fmac_f32_e32 v34, v137, v33
	v_med3_f32 v33, v11, 0, v173
	v_fmac_f32_e32 v34, v138, v32
	v_med3_f32 v32, v12, 0, v173
	v_fmac_f32_e32 v34, v139, v33
	v_mfma_f32_32x32x16_bf16 v[16:31], v[104:107], v[206:209], v[16:31]
	ds_read_b128 v[206:209], v239 offset:26304
	v_med3_f32 v33, v13, 0, v173
	v_fmac_f32_e32 v34, v140, v32
	v_med3_f32 v32, v14, 0, v173
	v_fmac_f32_e32 v34, v141, v33
	v_mfma_f32_32x32x16_bf16 v[16:31], v[108:111], v[210:213], v[16:31]
	ds_read_b128 v[210:213], v239 offset:26336
	v_med3_f32 v33, v15, 0, v173
	v_fmac_f32_e32 v34, v142, v32
	v_fmac_f32_e32 v34, v143, v33
	global_store_dword v[234:235], v34, off offset:0
	s_waitcnt lgkmcnt(7)
	v_mfma_f32_32x32x16_bf16 v[0:15], v[48:51], v[182:185], 0
	s_waitcnt lgkmcnt(6)
	v_mfma_f32_32x32x16_bf16 v[0:15], v[52:55], v[186:189], v[0:15]
	s_nop 2
	v_med3_f32 v32, v16, 0, v173
	v_med3_f32 v33, v17, 0, v173
	v_fma_f32 v35, v144, v32, 0
	v_med3_f32 v32, v18, 0, v173
	v_fmac_f32_e32 v35, v145, v33
	s_waitcnt lgkmcnt(5)
	v_mfma_f32_32x32x16_bf16 v[0:15], v[56:59], v[190:193], v[0:15]
	v_med3_f32 v33, v19, 0, v173
	v_fmac_f32_e32 v35, v146, v32
	v_med3_f32 v32, v20, 0, v173
	v_fmac_f32_e32 v35, v147, v33
	v_med3_f32 v33, v21, 0, v173
	s_waitcnt lgkmcnt(4)
	v_mfma_f32_32x32x16_bf16 v[0:15], v[60:63], v[194:197], v[0:15]
	v_fmac_f32_e32 v35, v148, v32
	v_med3_f32 v32, v22, 0, v173
	v_fmac_f32_e32 v35, v149, v33
	v_med3_f32 v33, v23, 0, v173
	v_fmac_f32_e32 v35, v150, v32
	s_waitcnt lgkmcnt(3)
	v_mfma_f32_32x32x16_bf16 v[0:15], v[64:67], v[198:201], v[0:15]
	v_med3_f32 v32, v24, 0, v173
	v_fmac_f32_e32 v35, v151, v33
	v_med3_f32 v33, v25, 0, v173
	v_fmac_f32_e32 v35, v152, v32
	v_med3_f32 v32, v26, 0, v173
	s_waitcnt lgkmcnt(2)
	v_mfma_f32_32x32x16_bf16 v[0:15], v[68:71], v[202:205], v[0:15]
	v_fmac_f32_e32 v35, v153, v33
	v_med3_f32 v33, v27, 0, v173
	v_fmac_f32_e32 v35, v154, v32
	v_med3_f32 v32, v28, 0, v173
	v_fmac_f32_e32 v35, v155, v33
	s_waitcnt lgkmcnt(1)
	v_mfma_f32_32x32x16_bf16 v[0:15], v[72:75], v[206:209], v[0:15]
	v_med3_f32 v33, v29, 0, v173
	v_fmac_f32_e32 v35, v156, v32
	v_med3_f32 v32, v30, 0, v173
	v_fmac_f32_e32 v35, v157, v33
	s_waitcnt lgkmcnt(0)
	v_mfma_f32_32x32x16_bf16 v[0:15], v[76:79], v[210:213], v[0:15]
	v_med3_f32 v33, v31, 0, v173
	v_fmac_f32_e32 v35, v158, v32
	v_fmac_f32_e32 v35, v159, v33
	global_store_dword v[236:237], v35, off offset:0
	s_barrier
; DI void indexer_unit(unsigned char* ws, LAS unsigned char* lds, int b, int blk, float* scratch, int wave) {
;     ...
;     for (int kt = 0; kt < nk; kt += 2) {
;         IDX_TILE(kt, st0, st1, su0, su1);
;         if (kt + 1 < nk) IDX_TILE(kt + 1, su0, su1, st0, st1);
;     }
	v_mfma_f32_32x32x16_bf16 v[16:31], v[80:83], v[182:185], 0
	ds_read_b128 v[182:185], v238
	v_mfma_f32_32x32x16_bf16 v[16:31], v[84:87], v[186:189], v[16:31]
	ds_read_b128 v[186:189], v238 offset:32
	s_nop 2
	v_med3_f32 v32, v0, 0, v173
	v_med3_f32 v33, v1, 0, v173
	v_fma_f32 v34, v128, v32, 0
	v_med3_f32 v32, v2, 0, v173
	v_fmac_f32_e32 v34, v129, v33
	v_mfma_f32_32x32x16_bf16 v[16:31], v[88:91], v[190:193], v[16:31]
	ds_read_b128 v[190:193], v238 offset:64
	v_med3_f32 v33, v3, 0, v173
	v_fmac_f32_e32 v34, v130, v32
	v_med3_f32 v32, v4, 0, v173
	v_fmac_f32_e32 v34, v131, v33
	v_med3_f32 v33, v5, 0, v173
	v_mfma_f32_32x32x16_bf16 v[16:31], v[92:95], v[194:197], v[16:31]
	ds_read_b128 v[194:197], v238 offset:96
	v_fmac_f32_e32 v34, v132, v32
	v_med3_f32 v32, v6, 0, v173
	v_fmac_f32_e32 v34, v133, v33
	v_med3_f32 v33, v7, 0, v173
	v_fmac_f32_e32 v34, v134, v32
	v_mfma_f32_32x32x16_bf16 v[16:31], v[96:99], v[198:201], v[16:31]
	ds_read_b128 v[198:201], v238 offset:128
	v_med3_f32 v32, v8, 0, v173
	v_fmac_f32_e32 v34, v135, v33
	v_med3_f32 v33, v9, 0, v173
	v_fmac_f32_e32 v34, v136, v32
	v_med3_f32 v32, v10, 0, v173
	v_mfma_f32_32x32x16_bf16 v[16:31], v[100:103], v[202:205], v[16:31]
	ds_read_b128 v[202:205], v238 offset:160
	v_fmac_f32_e32 v34, v137, v33
	v_med3_f32 v33, v11, 0, v173
	v_fmac_f32_e32 v34, v138, v32
	v_med3_f32 v32, v12, 0, v173
	v_fmac_f32_e32 v34, v139, v33
	v_mfma_f32_32x32x16_bf16 v[16:31], v[104:107], v[206:209], v[16:31]
	ds_read_b128 v[206:209], v238 offset:192
	v_med3_f32 v33, v13, 0, v173
	v_fmac_f32_e32 v34, v140, v32
	v_med3_f32 v32, v14, 0, v173
	v_fmac_f32_e32 v34, v141, v33
	v_mfma_f32_32x32x16_bf16 v[16:31], v[108:111], v[210:213], v[16:31]
	ds_read_b128 v[210:213], v238 offset:224
	v_med3_f32 v33, v15, 0, v173
	v_fmac_f32_e32 v34, v142, v32
	v_fmac_f32_e32 v34, v143, v33
	global_store_dword v[234:235], v34, off offset:128
	v_lshl_add_u64 v[234:235], v[234:235], 0, s[100:101]
	v_lshl_add_u64 v[236:237], v[236:237], 0, s[100:101]
	s_add_i32 s8, s8, -1
	s_cmp_lg_u32 s8, 0
	s_cbranch_scc1 .Lidx_loop
.Lidx_done:
	s_nop 11
	v_med3_f32 v32, v16, 0, v173
	v_med3_f32 v33, v17, 0, v173
	v_fma_f32 v35, v144, v32, 0
	v_med3_f32 v32, v18, 0, v173
	v_fmac_f32_e32 v35, v145, v33
	v_med3_f32 v33, v19, 0, v173
	v_fmac_f32_e32 v35, v146, v32
	v_med3_f32 v32, v20, 0, v173
	v_fmac_f32_e32 v35, v147, v33
	v_med3_f32 v33, v21, 0, v173
	v_fmac_f32_e32 v35, v148, v32
	v_med3_f32 v32, v22, 0, v173
	v_fmac_f32_e32 v35, v149, v33
	v_med3_f32 v33, v23, 0, v173
	v_fmac_f32_e32 v35, v150, v32
	v_med3_f32 v32, v24, 0, v173
	v_fmac_f32_e32 v35, v151, v33
	v_med3_f32 v33, v25, 0, v173
	v_fmac_f32_e32 v35, v152, v32
	v_med3_f32 v32, v26, 0, v173
	v_fmac_f32_e32 v35, v153, v33
	v_med3_f32 v33, v27, 0, v173
	v_fmac_f32_e32 v35, v154, v32
	v_med3_f32 v32, v28, 0, v173
	v_fmac_f32_e32 v35, v155, v33
	v_med3_f32 v33, v29, 0, v173
	v_fmac_f32_e32 v35, v156, v32
	v_med3_f32 v32, v30, 0, v173
	v_fmac_f32_e32 v35, v157, v33
	v_med3_f32 v33, v31, 0, v173
	v_fmac_f32_e32 v35, v158, v32
	v_fmac_f32_e32 v35, v159, v33
	global_store_dword v[236:237], v35, off offset:-384

; __device__ __forceinline__ int lane_opaque() { int l; asm volatile("v_mbcnt_lo_u32_b32 %0, -1, 0\n\tv_mbcnt_hi_u32_b32 %0, -1, %0" : "=v"(l)); return l; }
; DI unsigned fkey(float f) { unsigned u = __builtin_bit_cast(unsigned, f); if (u == 0x80000000u) u = 0u; return (u & 0x80000000u) ? ~u : (u | 0x80000000u); }
; DI void select_unit(unsigned char* ws, LAS unsigned char* lds, int b, int blk, const float* scratch, int wave) {
;     ...
;     for (int qq = 0; qq < 4; ++qq) {
;         const int lane = lane_opaque(); const unsigned long long lt_mask = (1ull << lane) - 1ull;
;         const int ql = wave * 4 + qq, t = blk * 32 + ql, n = t + 1;
;         const float* sc = scratch + (size_t)ql * SEQ; int* out = idx + (size_t)(b * SEQ + t) * TOPK;
;         if (n <= TOPK) { for (int e = lane; e < TOPK; e += 64) out[e] = (e < n) ? e : 0; continue; }
;         const int n4 = (n + 3) >> 2;
;         v4u key[32];
; #pragma unroll
;         for (int j = 0; j < 32; ++j) { key[j] = (v4u){0u, 0u, 0u, 0u};
;             if (64 * j < n4) { const int gi = 64 * j + lane; if (gi < n4) { const f32x4 v = *(const f32x4*)(sc + 4 * gi); const int e0 = 4 * gi;
;                 key[j].x = fkey(v[0]); key[j].y = (e0 + 1 < n) ? fkey(v[1]) : 0u; key[j].z = (e0 + 2 < n) ? fkey(v[2]) : 0u; key[j].w = (e0 + 3 < n) ? fkey(v[3]) : 0u; } } }
.LBB0_528:
	s_add_i32 s76, s91, s80
	s_add_i32 s33, s76, s90
	s_add_i32 s0, s33, s88
	s_ashr_i32 s1, s0, 31
	s_lshl_b64 s[0:1], s[0:1], 10
	s_add_u32 s96, s82, s0
	s_addc_u32 s97, s81, s1
	s_cmpk_gt_u32 s33, 0xff
	s_mov_b64 s[0:1], -1
	v_mbcnt_lo_u32_b32 v0, -1, 0
	v_mbcnt_hi_u32_b32 v0, -1, v0
	s_cbranch_scc0 .LBB0_1984
	s_lshl_b64 s[0:1], s[76:77], 15
	v_readlane_b32 s2, v254, 25
	s_add_u32 s18, s2, s0
	v_readlane_b32 s0, v254, 26
	s_addc_u32 s19, s0, s1
	s_add_i32 s0, s33, 4
	s_lshr_b32 s46, s0, 2
	v_lshlrev_b32_e32 v2, 2, v0
	v_cmp_gt_i32_e32 vcc, s46, v0
	s_waitcnt vmcnt(4)
	v_mov_b32_e32 v127, 0
	v_or_b32_e32 v132, 2, v2
	v_or_b32_e32 v131, 3, v2
	v_mov_b32_e32 v133, 0
	v_mov_b32_e32 v134, 0
	v_mov_b32_e32 v135, 0
	v_mov_b32_e32 v136, 0
	v_mov_b32_e32 v214, v2
	v_mov_b32_e32 v215, 0
	s_mov_b64 s[98:99], 0x1000
	v_lshl_add_u64 v[214:215], v[214:215], 2, s[18:19]
	global_load_dword v216, v[214:215], off
	s_cmpk_gt_i32 s46, 0x40
	s_cbranch_scc0 .Lsel_pf_done
	global_load_dword v217, v[214:215], off offset:1024
	s_cmpk_gt_i32 s46, 0x80
	s_cbranch_scc0 .Lsel_pf_done
	global_load_dword v218, v[214:215], off offset:2048
	s_cmpk_gt_i32 s46, 0xc0
	s_cbranch_scc0 .Lsel_pf_done
	global_load_dword v219, v[214:215], off offset:3072
	v_lshl_add_u64 v[214:215], v[214:215], 0, s[98:99]
	s_cmpk_gt_i32 s46, 0x100
	s_cbranch_scc0 .Lsel_pf_done
	global_load_dword v220, v[214:215], off
	s_cmpk_gt_i32 s46, 0x140
	s_cbranch_scc0 .Lsel_pf_done
	global_load_dword v221, v[214:215], off offset:1024
	s_cmpk_gt_i32 s46, 0x180
	s_cbranch_scc0 .Lsel_pf_done
	global_load_dword v222, v[214:215], off offset:2048
	s_cmpk_gt_i32 s46, 0x1c0
	s_cbranch_scc0 .Lsel_pf_done
	global_load_dword v223, v[214:215], off offset:3072
	v_lshl_add_u64 v[214:215], v[214:215], 0, s[98:99]
	s_cmpk_gt_i32 s46, 0x200
	s_cbranch_scc0 .Lsel_pf_done
	global_load_dword v224, v[214:215], off
	s_cmpk_gt_i32 s46, 0x240
	s_cbranch_scc0 .Lsel_pf_done
	global_load_dword v225, v[214:215], off offset:1024
	s_cmpk_gt_i32 s46, 0x280
	s_cbranch_scc0 .Lsel_pf_done
	global_load_dword v226, v[214:215], off offset:2048
	s_cmpk_gt_i32 s46, 0x2c0
	s_cbranch_scc0 .Lsel_pf_done
	global_load_dword v227, v[214:215], off offset:3072
	v_lshl_add_u64 v[214:215], v[214:215], 0, s[98:99]
	s_cmpk_gt_i32 s46, 0x300
	s_cbranch_scc0 .Lsel_pf_done
	global_load_dword v228, v[214:215], off
	s_cmpk_gt_i32 s46, 0x340
	s_cbranch_scc0 .Lsel_pf_done
	global_load_dword v229, v[214:215], off offset:1024
	s_cmpk_gt_i32 s46, 0x380
	s_cbranch_scc0 .Lsel_pf_done
	global_load_dword v230, v[214:215], off offset:2048
	s_cmpk_gt_i32 s46, 0x3c0
	s_cbranch_scc0 .Lsel_pf_done
	global_load_dword v231, v[214:215], off offset:3072
	v_lshl_add_u64 v[214:215], v[214:215], 0, s[98:99]
	s_cmpk_gt_i32 s46, 0x400
	s_cbranch_scc0 .Lsel_pf_done
	global_load_dword v232, v[214:215], off
	s_cmpk_gt_i32 s46, 0x440
	s_cbranch_scc0 .Lsel_pf_done
	global_load_dword v233, v[214:215], off offset:1024
	s_cmpk_gt_i32 s46, 0x480
	s_cbranch_scc0 .Lsel_pf_done
	global_load_dword v234, v[214:215], off offset:2048
	s_cmpk_gt_i32 s46, 0x4c0
	s_cbranch_scc0 .Lsel_pf_done
	global_load_dword v235, v[214:215], off offset:3072
	v_lshl_add_u64 v[214:215], v[214:215], 0, s[98:99]
	s_cmpk_gt_i32 s46, 0x500
	s_cbranch_scc0 .Lsel_pf_done
	global_load_dword v236, v[214:215], off
	s_cmpk_gt_i32 s46, 0x540
	s_cbranch_scc0 .Lsel_pf_done
	global_load_dword v237, v[214:215], off offset:1024
	s_cmpk_gt_i32 s46, 0x580
	s_cbranch_scc0 .Lsel_pf_done
	global_load_dword v238, v[214:215], off offset:2048
	s_cmpk_gt_i32 s46, 0x5c0
	s_cbranch_scc0 .Lsel_pf_done
	global_load_dword v239, v[214:215], off offset:3072
	v_lshl_add_u64 v[214:215], v[214:215], 0, s[98:99]
	s_cmpk_gt_i32 s46, 0x600
	s_cbranch_scc0 .Lsel_pf_done
	global_load_dword v240, v[214:215], off
	s_cmpk_gt_i32 s46, 0x640
	s_cbranch_scc0 .Lsel_pf_done
	global_load_dword v241, v[214:215], off offset:1024
	s_cmpk_gt_i32 s46, 0x680
	s_cbranch_scc0 .Lsel_pf_done
	global_load_dword v242, v[214:215], off offset:2048
	s_cmpk_gt_i32 s46, 0x6c0
	s_cbranch_scc0 .Lsel_pf_done
	global_load_dword v243, v[214:215], off offset:3072
	v_lshl_add_u64 v[214:215], v[214:215], 0, s[98:99]
	s_cmpk_gt_i32 s46, 0x700
	s_cbranch_scc0 .Lsel_pf_done
	global_load_dword v244, v[214:215], off
	s_cmpk_gt_i32 s46, 0x740
	s_cbranch_scc0 .Lsel_pf_done
	global_load_dword v245, v[214:215], off offset:1024
	s_cmpk_gt_i32 s46, 0x780
	s_cbranch_scc0 .Lsel_pf_done
	global_load_dword v246, v[214:215], off offset:2048
	s_cmpk_gt_i32 s46, 0x7c0
	s_cbranch_scc0 .Lsel_pf_done
	global_load_dword v247, v[214:215], off offset:3072
.Lsel_pf_done:
	s_and_saveexec_b64 s[0:1], vcc
	s_brev_b32 s48, 1
	s_cbranch_execz .LBB0_531
	v_ashrrev_i32_e32 v3, 31, v2
	v_lshl_add_u64 v[4:5], v[2:3], 2, s[18:19]
	global_load_dwordx4 v[4:7], v[4:5], off
	v_or_b32_e32 v1, 2, v2
	v_or_b32_e32 v3, 3, v2
	s_waitcnt vmcnt(0)
	v_cmp_ne_u32_e32 vcc, s48, v4
	s_nop 1
	v_cndmask_b32_e32 v4, 0, v4, vcc
	v_cmp_ne_u32_e32 vcc, s48, v5
	v_not_b32_e32 v8, v4
	s_nop 0
	v_cndmask_b32_e32 v5, 0, v5, vcc
	v_cmp_ne_u32_e32 vcc, s48, v6
	v_not_b32_e32 v9, v5
	s_nop 0
	v_cndmask_b32_e32 v6, 0, v6, vcc
	v_cmp_ne_u32_e32 vcc, s48, v7
	v_not_b32_e32 v10, v6
	s_nop 0
	v_cndmask_b32_e32 v7, 0, v7, vcc
	v_cmp_gt_i32_e32 vcc, 0, v4
	v_not_b32_e32 v11, v7
	s_nop 0
	v_cndmask_b32_e64 v133, -|v4|, v8, vcc
	v_cmp_gt_i32_e32 vcc, 0, v5
	s_nop 1
	v_cndmask_b32_e64 v4, -|v5|, v9, vcc
	v_cmp_gt_i32_e32 vcc, 0, v6
	s_nop 1
	v_cndmask_b32_e64 v5, -|v6|, v10, vcc
	v_cmp_gt_i32_e32 vcc, 0, v7
	s_nop 1
	v_cndmask_b32_e64 v6, -|v7|, v11, vcc
	v_cmp_gt_i32_e32 vcc, s33, v2
	s_nop 1
	v_cndmask_b32_e32 v134, 0, v4, vcc
	v_cmp_ge_i32_e32 vcc, s33, v1
	s_nop 1
	v_cndmask_b32_e32 v135, 0, v5, vcc
	v_cmp_ge_i32_e32 vcc, s33, v3
	s_nop 1
	v_cndmask_b32_e32 v136, 0, v6, vcc

; __global__ void __launch_bounds__(NWAVES * 64, 2) hybrid_fwd(Args args) {
	.amdhsa_kernel _Z10hybrid_fwd4Args
		.amdhsa_group_segment_fixed_size 0
		.amdhsa_private_segment_fixed_size 0
		.amdhsa_kernarg_size 536
		.amdhsa_user_sgpr_count 2
		.amdhsa_user_sgpr_dispatch_ptr 0
		.amdhsa_user_sgpr_queue_ptr 0
		.amdhsa_user_sgpr_kernarg_segment_ptr 1
		.amdhsa_user_sgpr_dispatch_id 0
		.amdhsa_user_sgpr_kernarg_preload_length 0
		.amdhsa_user_sgpr_kernarg_preload_offset 0
		.amdhsa_user_sgpr_private_segment_size 0
		.amdhsa_uses_dynamic_stack 0
		.amdhsa_enable_private_segment 0
		.amdhsa_system_sgpr_workgroup_id_x 1
		.amdhsa_system_sgpr_workgroup_id_y 0
		.amdhsa_system_sgpr_workgroup_id_z 0
		.amdhsa_system_sgpr_workgroup_info 0
		.amdhsa_system_vgpr_workitem_id 0
		.amdhsa_next_free_vgpr 255
		.amdhsa_next_free_sgpr 102
		.amdhsa_accum_offset 256
		.amdhsa_reserve_vcc 1
		.amdhsa_float_round_mode_32 0
		.amdhsa_float_round_mode_16_64 0
		.amdhsa_float_denorm_mode_32 3
		.amdhsa_float_denorm_mode_16_64 3
		.amdhsa_dx10_clamp 1
		.amdhsa_ieee_mode 1
		.amdhsa_fp16_overflow 0
		.amdhsa_tg_split 0
		.amdhsa_exception_fp_ieee_invalid_op 0
		.amdhsa_exception_fp_denorm_src 0
		.amdhsa_exception_fp_ieee_div_zero 0
		.amdhsa_exception_fp_ieee_overflow 0
		.amdhsa_exception_fp_ieee_underflow 0
		.amdhsa_exception_fp_ieee_inexact 0
		.amdhsa_exception_int_div_zero 0
	.end_amdhsa_kernel

; __global__ void __launch_bounds__(NWAVES * 64, 2) hybrid_fwd(Args args) {
amdhsa.kernels:
  - .agpr_count:     0
    .args:
      - .offset:         0
        .size:           280
        .value_kind:     by_value
      - .offset:         280
        .size:           4
        .value_kind:     hidden_block_count_x
      - .offset:         284
        .size:           4
        .value_kind:     hidden_block_count_y
      - .offset:         288
        .size:           4
        .value_kind:     hidden_block_count_z
      - .offset:         292
        .size:           2
        .value_kind:     hidden_group_size_x
      - .offset:         294
        .size:           2
        .value_kind:     hidden_group_size_y
      - .offset:         296
        .size:           2
        .value_kind:     hidden_group_size_z
      - .offset:         298
        .size:           2
        .value_kind:     hidden_remainder_x
      - .offset:         300
        .size:           2
        .value_kind:     hidden_remainder_y
      - .offset:         302
        .size:           2
        .value_kind:     hidden_remainder_z
      - .offset:         320
        .size:           8
        .value_kind:     hidden_global_offset_x
      - .offset:         328
        .size:           8
        .value_kind:     hidden_global_offset_y
      - .offset:         336
        .size:           8
        .value_kind:     hidden_global_offset_z
      - .offset:         344
        .size:           2
        .value_kind:     hidden_grid_dims
      - .offset:         400
        .size:           4
        .value_kind:     hidden_dynamic_lds_size
    .group_segment_fixed_size: 0
    .kernarg_segment_align: 8
    .kernarg_segment_size: 536
    .language:       OpenCL C
    .language_version:
      - 2
      - 0
    .max_flat_workgroup_size: 512
    .name:           _Z10hybrid_fwd4Args
    .private_segment_fixed_size: 0
    .sgpr_count:     108
    .sgpr_spill_count: 172
    .symbol:         _Z10hybrid_fwd4Args.kd
    .uniform_work_group_size: 1
    .uses_dynamic_stack: false
    .vgpr_count:     255
    .vgpr_spill_count: 0
    .wavefront_size: 64
